# wait-relaxation removed (no measurable gain, fewer moving parts); m0 save/restore around LDS-DMA dropped in attention phases
# speedup vs baseline: 1.0153x; 1.0153x over previous
.LBB0_519:
	s_and_b32 s4, s81, 7
	s_lshl_b32 s7, s75, 24
	s_lshl_b32 s34, s4, 8
	s_mul_i32 s4, s79, 0x600
	s_add_u32 s4, s8, s4
	s_addc_u32 s5, s9, 0
	s_mul_i32 s6, s74, 0xc0
	s_add_u32 s38, s4, s6
	s_addc_u32 s39, s5, 0
	s_lshl_b32 s4, s83, 11
	s_add_u32 s4, s12, s4
	s_addc_u32 s5, s13, 0
	s_lshl_b32 s6, s74, 8
	s_add_u32 s40, s4, s6
	v_readfirstlane_b32 s6, v192
	s_addc_u32 s41, s5, 0
	s_lshr_b32 s30, s6, 6
	s_lshl_b32 s42, s83, 6
	s_lshl_b32 s72, s30, 5
	s_mul_i32 s4, s30, 0xc000
	s_mul_hi_u32 s5, s72, 0x600
	s_add_u32 s4, s38, s4
	s_addc_u32 s5, s39, s5
	v_lshl_add_u64 v[2:3], s[40:41], 0, v[194:195]
	s_lshl_b32 s18, s30, 4
	s_mov_b32 s19, s73
	s_mov_b32 s43, s73
	s_and_b32 s35, s6, 0x3fffffc0
	v_lshl_add_u64 v[182:183], v[2:3], 0, s[18:19]
	s_bfe_u32 s19, s6, 0x20006
	s_lshr_b32 s6, s6, 2
	v_lshl_add_u64 v[2:3], v[196:197], 0, s[42:43]
	s_lshl_b32 s42, s19, 4
	s_and_b32 s70, s6, 0x3fffffc0
	s_lshl_b32 s85, s30, 10
	v_lshl_or_b32 v0, s19, 15, v239
	s_cmp_lg_u32 0, -1
	v_lshl_add_u64 v[226:227], v[2:3], 0, s[42:43]
	v_lshl_add_u64 v[2:3], s[40:41], 0, v[0:1]
	s_mov_b32 s71, s73
	s_cselect_b32 s6, 0, 0
	s_lshl_b32 s86, s19, 10
	v_lshl_add_u64 v[2:3], v[2:3], 0, s[70:71]
	v_mov_b32_e32 v221, v1
	s_add_i32 s87, s85, s6
	s_mov_b32 m0, s87
	s_nop 0
	global_load_lds_dwordx4 v[182:183], off
	s_bitset1_b32 s86, 13
	v_lshl_add_u64 v[10:11], v[2:3], 0, v[220:221]
	s_mov_b64 s[40:41], 0x80
	s_add_i32 s84, s86, s6
	s_mov_b32 m0, s84
	s_nop 0
	global_load_lds_dwordx4 v[226:227], off
	v_lshl_add_u64 v[222:223], v[10:11], 0, s[40:41]
	s_add_i32 s71, s87, 0x9000
	s_mov_b32 m0, s71
	s_nop 0
	global_load_lds_dwordx4 v[222:223], off
	s_add_i32 s19, s6, 0x3000
	v_lshl_add_u64 v[2:3], v[182:183], 0, s[20:21]
	s_add_i32 s37, s85, s19
	s_mov_b32 m0, s37
	s_nop 0
	global_load_lds_dwordx4 v[2:3], off
	s_mov_b64 s[40:41], 0x1000
	v_lshl_add_u64 v[2:3], v[226:227], 0, s[40:41]
	s_add_i32 s19, s86, s19
	s_mov_b32 m0, s19
	s_nop 0
	global_load_lds_dwordx4 v[2:3], off
	v_or_b32_e32 v4, s72, v191
	v_mov_b64_e32 v[2:3], s[38:39]
	s_movk_i32 s19, 0x600
	v_mad_u64_u32 v[2:3], s[38:39], v4, s19, v[2:3]
	v_mov_b32_e32 v217, v1
	v_lshl_add_u64 v[2:3], v[2:3], 0, v[216:217]
	global_load_dwordx4 v[6:9], v[2:3], off offset:128
	v_or_b32_e32 v4, s36, v191
	v_add_u32_e32 v4, s72, v4
	v_lshrrev_b32_e32 v5, 6, v4
	v_cvt_f32_u32_e32 v16, v5
	v_cmp_lt_i32_e32 vcc, v243, v244
	v_and_b32_e32 v29, 63, v4
	s_mov_b32 s36, 0x3c08839e
	v_cndmask_b32_e32 v5, v242, v243, vcc
	v_mul_f32_e32 v17, 0x3ea1e89b, v16
	v_lshlrev_b32_e32 v28, 2, v5
	v_mul_f32_e32 v4, 0x3f22f983, v16
	v_mul_f32_e32 v5, 0x3f22f983, v17
	v_rndne_f32_e32 v4, v4
	v_rndne_f32_e32 v5, v5
	v_pk_fma_f32 v[18:19], v[4:5], s[22:23], v[16:17] op_sel_hi:[1,0,1] neg_lo:[1,0,0] neg_hi:[1,0,0]
	v_mov_b64_e32 v[12:13], s[36:37]
	v_pk_fma_f32 v[18:19], v[4:5], s[24:25], v[18:19] op_sel_hi:[1,0,1] neg_lo:[1,0,0] neg_hi:[1,0,0]
	s_mov_b32 s36, 0xbab6061a
	v_pk_fma_f32 v[18:19], v[4:5], s[26:27], v[18:19] op_sel_hi:[1,0,1] neg_lo:[1,0,0] neg_hi:[1,0,0]
	v_mov_b64_e32 v[14:15], s[36:37]
	v_pk_mul_f32 v[20:21], v[18:19], v[18:19]
	v_cvt_i32_f32_e32 v30, v4
	v_pk_fma_f32 v[24:25], v[20:21], s[76:77], v[12:13] op_sel_hi:[1,0,0] neg_lo:[1,0,0] neg_hi:[1,0,0]
	v_cvt_i32_f32_e32 v17, v5
	v_pk_mul_f32 v[22:23], v[18:19], v[20:21]
	v_pk_fma_f32 v[26:27], v[20:21], s[80:81], v[14:15] op_sel_hi:[1,0,0]
	v_pk_fma_f32 v[24:25], v[20:21], v[24:25], s[78:79] op_sel_hi:[1,1,0]
	global_load_dwordx4 v[110:113], v240, s[4:5]
	global_load_dwordx4 v[106:109], v240, s[4:5] offset:32
	global_load_dwordx4 v[102:105], v240, s[4:5] offset:64
	global_load_dwordx4 v[98:101], v240, s[4:5] offset:96
	v_pk_fma_f32 v[18:19], v[22:23], v[24:25], v[18:19]
	v_pk_fma_f32 v[22:23], v[20:21], v[26:27], s[82:83] op_sel_hi:[1,1,0]
	global_load_dwordx4 v[2:5], v[2:3], off offset:160
	v_pk_fma_f32 v[22:23], v[20:21], v[22:23], -0.5 op_sel_hi:[1,1,0]
	v_and_b32_e32 v25, 2, v30
	v_pk_fma_f32 v[20:21], v[20:21], v[22:23], 1.0 op_sel_hi:[1,1,0]
	v_and_b32_e32 v23, 1, v30
	v_and_b32_e32 v22, 1, v17
	v_cmp_eq_u32_e32 vcc, 0, v23
	v_cmp_eq_u32_e64 s[4:5], 0, v22
	s_mov_b32 s36, 0x3dcccccd
	v_cndmask_b32_e32 v23, v20, v18, vcc
	v_cndmask_b32_e32 v20, v18, v20, vcc
	v_and_b32_e32 v18, 2, v17
	v_cndmask_b32_e64 v22, v21, v19, s[4:5]
	v_cmp_eq_u32_e32 vcc, 0, v18
	v_add_u32_e32 v17, 1, v17
	v_cndmask_b32_e64 v21, v19, v21, s[4:5]
	v_cndmask_b32_e64 v19, -v22, v22, vcc
	v_cmp_eq_u32_e32 vcc, 0, v25
	v_add_u32_e32 v22, 1, v30
	v_and_b32_e32 v17, 2, v17
	v_cndmask_b32_e64 v18, -v23, v23, vcc
	v_and_b32_e32 v22, 2, v22
	v_cmp_eq_u32_e32 vcc, 0, v17
	s_mov_b32 s37, 0x3d0186e3
	s_mov_b32 s38, 0x3c23d70b
	v_cndmask_b32_e64 v21, -v21, v21, vcc
	v_cmp_eq_u32_e32 vcc, 0, v22
	s_mov_b32 s39, 0x3b4f3e39
	s_mov_b32 s40, 0x3a831270
	v_cndmask_b32_e64 v20, -v20, v20, vcc
	s_mov_b32 s41, 0x39a5cb61
	s_addk_i32 s6, 0x6000
	s_or_b32 s7, s7, s34
	s_mov_b32 s88, -1
	s_movk_i32 s89, 0x6000
	v_lshl_add_u64 v[178:179], v[226:227], 0, s[94:95]
	v_lshl_add_u64 v[180:181], v[182:183], 0, s[96:97]
	s_waitcnt vmcnt(5)
	ds_bpermute_b32 v24, v28, v6
	v_and_b32_e32 v23, 0xffff0000, v6
	v_lshlrev_b32_e32 v22, 16, v6
	ds_bpermute_b32 v31, v28, v7
	ds_bpermute_b32 v32, v28, v8
	s_waitcnt lgkmcnt(2)
	v_and_b32_e32 v25, 0xffff0000, v24
	v_lshlrev_b32_e32 v24, 16, v24
	v_pk_mul_f32 v[18:19], v[18:19], v[24:25]
	ds_bpermute_b32 v33, v28, v9
	v_cndmask_b32_e64 v19, v19, -v19, s[0:1]
	v_cndmask_b32_e64 v18, v18, -v18, s[0:1]
	v_pk_fma_f32 v[18:19], v[20:21], v[22:23], v[18:19]
	v_pk_mul_f32 v[20:21], v[16:17], s[36:37] op_sel_hi:[0,1]
	v_mul_f32_e32 v6, 0x3f22f983, v20
	v_rndne_f32_e32 v22, v6
	v_mul_f32_e32 v6, 0x3f22f983, v21
	v_rndne_f32_e32 v23, v6
	v_pk_fma_f32 v[20:21], v[22:23], s[22:23], v[20:21] op_sel_hi:[1,0,1] neg_lo:[1,0,0] neg_hi:[1,0,0]
	v_cvt_i32_f32_e32 v6, v23
	v_pk_fma_f32 v[20:21], v[22:23], s[24:25], v[20:21] op_sel_hi:[1,0,1] neg_lo:[1,0,0] neg_hi:[1,0,0]
	v_cvt_i32_f32_e32 v17, v22
	v_pk_fma_f32 v[20:21], v[22:23], s[26:27], v[20:21] op_sel_hi:[1,0,1] neg_lo:[1,0,0] neg_hi:[1,0,0]
	v_cvt_pk_bf16_f32 v114, v18, v19
	v_pk_mul_f32 v[24:25], v[20:21], v[20:21]
	s_waitcnt vmcnt(0)
	ds_bpermute_b32 v40, v28, v4
	v_pk_fma_f32 v[26:27], v[24:25], s[76:77], v[12:13] op_sel_hi:[1,0,0] neg_lo:[1,0,0] neg_hi:[1,0,0]
	v_pk_mul_f32 v[22:23], v[20:21], v[24:25]
	v_pk_fma_f32 v[26:27], v[24:25], v[26:27], s[78:79] op_sel_hi:[1,1,0]
	ds_bpermute_b32 v62, v28, v5
	v_pk_fma_f32 v[20:21], v[22:23], v[26:27], v[20:21]
	v_pk_fma_f32 v[22:23], v[24:25], s[80:81], v[14:15] op_sel_hi:[1,0,0]
	v_and_b32_e32 v26, 2, v17
	v_pk_fma_f32 v[22:23], v[24:25], v[22:23], s[82:83] op_sel_hi:[1,1,0]
	s_nop 0
	v_pk_fma_f32 v[22:23], v[24:25], v[22:23], -0.5 op_sel_hi:[1,1,0]
	s_nop 0
	v_pk_fma_f32 v[22:23], v[24:25], v[22:23], 1.0 op_sel_hi:[1,1,0]
	v_and_b32_e32 v25, 1, v17
	v_and_b32_e32 v24, 1, v6
	v_cmp_eq_u32_e32 vcc, 0, v25
	v_cmp_eq_u32_e64 s[4:5], 0, v24
	v_add_u32_e32 v17, 1, v17
	v_cndmask_b32_e32 v25, v22, v20, vcc
	v_cndmask_b32_e32 v22, v20, v22, vcc
	v_and_b32_e32 v20, 2, v6
	v_cndmask_b32_e64 v24, v23, v21, s[4:5]
	v_cmp_eq_u32_e32 vcc, 0, v20
	v_add_u32_e32 v6, 1, v6
	v_cndmask_b32_e64 v23, v21, v23, s[4:5]
	v_cndmask_b32_e64 v21, -v24, v24, vcc
	v_cmp_eq_u32_e32 vcc, 0, v26
	v_and_b32_e32 v6, 2, v6
	v_and_b32_e32 v17, 2, v17
	v_cndmask_b32_e64 v20, -v25, v25, vcc
	v_cmp_eq_u32_e32 vcc, 0, v6
	v_and_b32_e32 v25, 0xffff0000, v7
	v_lshlrev_b32_e32 v24, 16, v7
	s_waitcnt lgkmcnt(4)
	v_and_b32_e32 v7, 0xffff0000, v31
	v_lshlrev_b32_e32 v6, 16, v31
	v_cndmask_b32_e64 v23, -v23, v23, vcc
	v_cmp_eq_u32_e32 vcc, 0, v17
	v_pk_mul_f32 v[6:7], v[20:21], v[6:7]
	v_pk_mul_f32 v[20:21], v[16:17], s[38:39] op_sel_hi:[0,1]
	v_cndmask_b32_e64 v22, -v22, v22, vcc
	v_cndmask_b32_e64 v7, v7, -v7, s[0:1]
	v_cndmask_b32_e64 v6, v6, -v6, s[0:1]
	v_mul_f32_e32 v17, 0x3f22f983, v20
	v_pk_fma_f32 v[6:7], v[22:23], v[24:25], v[6:7]
	v_rndne_f32_e32 v22, v17
	v_mul_f32_e32 v17, 0x3f22f983, v21
	v_rndne_f32_e32 v23, v17
	v_pk_fma_f32 v[20:21], v[22:23], s[22:23], v[20:21] op_sel_hi:[1,0,1] neg_lo:[1,0,0] neg_hi:[1,0,0]
	v_cvt_i32_f32_e32 v17, v23
	v_pk_fma_f32 v[20:21], v[22:23], s[24:25], v[20:21] op_sel_hi:[1,0,1] neg_lo:[1,0,0] neg_hi:[1,0,0]
	v_cvt_i32_f32_e32 v30, v22
	v_pk_fma_f32 v[20:21], v[22:23], s[26:27], v[20:21] op_sel_hi:[1,0,1] neg_lo:[1,0,0] neg_hi:[1,0,0]
	v_cvt_pk_bf16_f32 v115, v6, v7
	v_pk_mul_f32 v[24:25], v[20:21], v[20:21]
	s_nop 0
	v_pk_fma_f32 v[26:27], v[24:25], s[76:77], v[12:13] op_sel_hi:[1,0,0] neg_lo:[1,0,0] neg_hi:[1,0,0]
	v_pk_mul_f32 v[22:23], v[20:21], v[24:25]
	v_pk_fma_f32 v[26:27], v[24:25], v[26:27], s[78:79] op_sel_hi:[1,1,0]
	s_nop 0
	v_pk_fma_f32 v[20:21], v[22:23], v[26:27], v[20:21]
	v_pk_fma_f32 v[22:23], v[24:25], s[80:81], v[14:15] op_sel_hi:[1,0,0]
	v_and_b32_e32 v26, 2, v30
	v_pk_fma_f32 v[22:23], v[24:25], v[22:23], s[82:83] op_sel_hi:[1,1,0]
	s_waitcnt lgkmcnt(3)
	v_and_b32_e32 v27, 0xffff0000, v32
	v_pk_fma_f32 v[22:23], v[24:25], v[22:23], -0.5 op_sel_hi:[1,1,0]
	s_nop 0
	v_pk_fma_f32 v[22:23], v[24:25], v[22:23], 1.0 op_sel_hi:[1,1,0]
	v_and_b32_e32 v25, 1, v30
	v_and_b32_e32 v24, 1, v17
	v_cmp_eq_u32_e32 vcc, 0, v25
	v_cmp_eq_u32_e64 s[4:5], 0, v24
	s_nop 0
	v_cndmask_b32_e32 v25, v22, v20, vcc
	v_cndmask_b32_e32 v22, v20, v22, vcc
	v_and_b32_e32 v20, 2, v17
	v_cndmask_b32_e64 v24, v23, v21, s[4:5]
	v_cmp_eq_u32_e32 vcc, 0, v20
	v_add_u32_e32 v17, 1, v17
	v_cndmask_b32_e64 v23, v21, v23, s[4:5]
	v_cndmask_b32_e64 v21, -v24, v24, vcc
	v_cmp_eq_u32_e32 vcc, 0, v26
	v_add_u32_e32 v24, 1, v30
	v_and_b32_e32 v17, 2, v17
	v_cndmask_b32_e64 v20, -v25, v25, vcc
	v_and_b32_e32 v24, 2, v24
	v_cmp_eq_u32_e32 vcc, 0, v17
	v_lshlrev_b32_e32 v26, 16, v32
	v_pk_mul_f32 v[20:21], v[20:21], v[26:27]
	v_cndmask_b32_e64 v23, -v23, v23, vcc
	v_cmp_eq_u32_e32 vcc, 0, v24
	v_pk_mul_f32 v[16:17], v[16:17], s[40:41] op_sel_hi:[0,1]
	v_and_b32_e32 v25, 0xffff0000, v8
	v_cndmask_b32_e64 v22, -v22, v22, vcc
	v_lshlrev_b32_e32 v24, 16, v8
	v_cndmask_b32_e64 v21, v21, -v21, s[0:1]
	v_cndmask_b32_e64 v20, v20, -v20, s[0:1]
	v_mul_f32_e32 v8, 0x3f22f983, v16
	v_pk_fma_f32 v[20:21], v[22:23], v[24:25], v[20:21]
	v_rndne_f32_e32 v22, v8
	v_mul_f32_e32 v8, 0x3f22f983, v17
	v_rndne_f32_e32 v23, v8
	v_pk_fma_f32 v[16:17], v[22:23], s[22:23], v[16:17] op_sel_hi:[1,0,1] neg_lo:[1,0,0] neg_hi:[1,0,0]
	v_cvt_i32_f32_e32 v8, v23
	v_pk_fma_f32 v[16:17], v[22:23], s[24:25], v[16:17] op_sel_hi:[1,0,1] neg_lo:[1,0,0] neg_hi:[1,0,0]
	v_cvt_i32_f32_e32 v30, v22
	v_pk_fma_f32 v[16:17], v[22:23], s[26:27], v[16:17] op_sel_hi:[1,0,1] neg_lo:[1,0,0] neg_hi:[1,0,0]
	v_cvt_pk_bf16_f32 v116, v20, v21
	v_pk_mul_f32 v[24:25], v[16:17], v[16:17]
	s_nop 0
	v_pk_fma_f32 v[26:27], v[24:25], s[76:77], v[12:13] op_sel_hi:[1,0,0] neg_lo:[1,0,0] neg_hi:[1,0,0]
	v_pk_mul_f32 v[22:23], v[16:17], v[24:25]
	v_pk_fma_f32 v[26:27], v[24:25], v[26:27], s[78:79] op_sel_hi:[1,1,0]
	s_nop 0
	v_pk_fma_f32 v[16:17], v[22:23], v[26:27], v[16:17]
	v_pk_fma_f32 v[22:23], v[24:25], s[80:81], v[14:15] op_sel_hi:[1,0,0]
	v_and_b32_e32 v26, 2, v30
	v_pk_fma_f32 v[22:23], v[24:25], v[22:23], s[82:83] op_sel_hi:[1,1,0]
	s_nop 0
	v_pk_fma_f32 v[22:23], v[24:25], v[22:23], -0.5 op_sel_hi:[1,1,0]
	s_nop 0
	v_pk_fma_f32 v[22:23], v[24:25], v[22:23], 1.0 op_sel_hi:[1,1,0]
	v_and_b32_e32 v25, 1, v30
	v_and_b32_e32 v24, 1, v8
	v_cmp_eq_u32_e32 vcc, 0, v25
	v_cmp_eq_u32_e64 s[4:5], 0, v24
	s_nop 0
	v_cndmask_b32_e32 v25, v22, v16, vcc
	v_cndmask_b32_e32 v22, v16, v22, vcc
	v_and_b32_e32 v16, 2, v8
	v_cndmask_b32_e64 v24, v23, v17, s[4:5]
	v_cmp_eq_u32_e32 vcc, 0, v16
	v_add_u32_e32 v8, 1, v8
	v_cndmask_b32_e64 v23, v17, v23, s[4:5]
	v_cndmask_b32_e64 v17, -v24, v24, vcc
	v_cmp_eq_u32_e32 vcc, 0, v26
	v_add_u32_e32 v24, 1, v30
	v_and_b32_e32 v8, 2, v8
	v_cndmask_b32_e64 v16, -v25, v25, vcc
	v_and_b32_e32 v24, 2, v24
	v_cmp_eq_u32_e32 vcc, 0, v8
	v_and_b32_e32 v25, 0xffff0000, v9
	s_waitcnt lgkmcnt(2)
	v_lshlrev_b32_e32 v8, 16, v33
	v_cndmask_b32_e64 v23, -v23, v23, vcc
	v_cmp_eq_u32_e32 vcc, 0, v24
	v_lshlrev_b32_e32 v24, 16, v9
	v_and_b32_e32 v9, 0xffff0000, v33
	v_pk_mul_f32 v[8:9], v[16:17], v[8:9]
	v_cndmask_b32_e64 v22, -v22, v22, vcc
	v_cndmask_b32_e64 v9, v9, -v9, s[0:1]
	v_cndmask_b32_e64 v8, v8, -v8, s[0:1]
	v_pk_fma_f32 v[8:9], v[22:23], v[24:25], v[8:9]
	ds_bpermute_b32 v22, v28, v2
	v_cvt_pk_bf16_f32 v117, v8, v9
	v_cvt_f32_ubyte0_e32 v8, v29
	v_mul_f32_e32 v9, 0x3ea1e89b, v8
	v_mul_f32_e32 v6, 0x3f22f983, v8
	v_mul_f32_e32 v7, 0x3f22f983, v9
	v_rndne_f32_e32 v6, v6
	v_rndne_f32_e32 v7, v7
	v_pk_fma_f32 v[16:17], v[6:7], s[22:23], v[8:9] op_sel_hi:[1,0,1] neg_lo:[1,0,0] neg_hi:[1,0,0]
	v_cvt_i32_f32_e32 v9, v6
	v_pk_fma_f32 v[16:17], v[6:7], s[24:25], v[16:17] op_sel_hi:[1,0,1] neg_lo:[1,0,0] neg_hi:[1,0,0]
	v_cvt_i32_f32_e32 v23, v7
	v_pk_fma_f32 v[16:17], v[6:7], s[26:27], v[16:17] op_sel_hi:[1,0,1] neg_lo:[1,0,0] neg_hi:[1,0,0]
	ds_bpermute_b32 v24, v28, v3
	v_pk_mul_f32 v[18:19], v[16:17], v[16:17]
	s_nop 0
	v_pk_fma_f32 v[20:21], v[18:19], s[76:77], v[12:13] op_sel_hi:[1,0,0] neg_lo:[1,0,0] neg_hi:[1,0,0]
	v_pk_mul_f32 v[6:7], v[16:17], v[18:19]
	v_pk_fma_f32 v[20:21], v[18:19], v[20:21], s[78:79] op_sel_hi:[1,1,0]
	s_nop 0
	v_pk_fma_f32 v[6:7], v[6:7], v[20:21], v[16:17]
	v_pk_fma_f32 v[16:17], v[18:19], s[80:81], v[14:15] op_sel_hi:[1,0,0]
	v_and_b32_e32 v20, 2, v9
	v_pk_fma_f32 v[16:17], v[18:19], v[16:17], s[82:83] op_sel_hi:[1,1,0]
	s_waitcnt lgkmcnt(1)
	v_and_b32_e32 v21, 0xffff0000, v22
	v_pk_fma_f32 v[16:17], v[18:19], v[16:17], -0.5 op_sel_hi:[1,1,0]
	s_nop 0
	v_pk_fma_f32 v[16:17], v[18:19], v[16:17], 1.0 op_sel_hi:[1,1,0]
	v_and_b32_e32 v19, 1, v9
	v_and_b32_e32 v18, 1, v23
	v_cmp_eq_u32_e32 vcc, 0, v19
	v_cmp_eq_u32_e64 s[4:5], 0, v18
	v_add_u32_e32 v9, 1, v9
	v_cndmask_b32_e32 v19, v16, v6, vcc
	v_cndmask_b32_e32 v16, v6, v16, vcc
	v_and_b32_e32 v6, 2, v23
	v_cndmask_b32_e64 v18, v17, v7, s[4:5]
	v_cmp_eq_u32_e32 vcc, 0, v6
	v_cndmask_b32_e64 v17, v7, v17, s[4:5]
	v_and_b32_e32 v9, 2, v9
	v_cndmask_b32_e64 v7, -v18, v18, vcc
	v_add_u32_e32 v18, 1, v23
	v_cmp_eq_u32_e32 vcc, 0, v20
	v_and_b32_e32 v18, 2, v18
	v_lshlrev_b32_e32 v20, 16, v22
	v_cndmask_b32_e64 v6, -v19, v19, vcc
	v_cmp_eq_u32_e32 vcc, 0, v18
	v_pk_mul_f32 v[6:7], v[6:7], v[20:21]
	v_and_b32_e32 v19, 0xffff0000, v2
	v_cndmask_b32_e64 v17, -v17, v17, vcc
	v_cmp_eq_u32_e32 vcc, 0, v9
	v_lshlrev_b32_e32 v18, 16, v2
	v_cndmask_b32_e64 v7, v7, -v7, s[0:1]
	v_cndmask_b32_e64 v16, -v16, v16, vcc
	v_cndmask_b32_e64 v6, v6, -v6, s[0:1]
	v_pk_fma_f32 v[6:7], v[16:17], v[18:19], v[6:7]
	v_pk_mul_f32 v[16:17], v[8:9], s[36:37] op_sel_hi:[0,1]
	v_mul_f32_e32 v2, 0x3f22f983, v16
	v_rndne_f32_e32 v18, v2
	v_mul_f32_e32 v2, 0x3f22f983, v17
	v_rndne_f32_e32 v19, v2
	v_pk_fma_f32 v[16:17], v[18:19], s[22:23], v[16:17] op_sel_hi:[1,0,1] neg_lo:[1,0,0] neg_hi:[1,0,0]
	v_cvt_i32_f32_e32 v2, v19
	v_pk_fma_f32 v[16:17], v[18:19], s[24:25], v[16:17] op_sel_hi:[1,0,1] neg_lo:[1,0,0] neg_hi:[1,0,0]
	v_cvt_i32_f32_e32 v9, v18
	v_pk_fma_f32 v[16:17], v[18:19], s[26:27], v[16:17] op_sel_hi:[1,0,1] neg_lo:[1,0,0] neg_hi:[1,0,0]
	v_cvt_pk_bf16_f32 v126, v6, v7
	v_pk_mul_f32 v[20:21], v[16:17], v[16:17]
	s_mov_b32 s36, 0
	v_pk_fma_f32 v[22:23], v[20:21], s[76:77], v[12:13] op_sel_hi:[1,0,0] neg_lo:[1,0,0] neg_hi:[1,0,0]
	v_pk_mul_f32 v[18:19], v[16:17], v[20:21]
	v_pk_fma_f32 v[22:23], v[20:21], v[22:23], s[78:79] op_sel_hi:[1,1,0]
	s_mov_b32 s37, s36
	v_pk_fma_f32 v[16:17], v[18:19], v[22:23], v[16:17]
	v_pk_fma_f32 v[18:19], v[20:21], s[80:81], v[14:15] op_sel_hi:[1,0,0]
	v_and_b32_e32 v22, 2, v9
	v_pk_fma_f32 v[18:19], v[20:21], v[18:19], s[82:83] op_sel_hi:[1,1,0]
	s_mov_b32 s42, s36
	v_pk_fma_f32 v[18:19], v[20:21], v[18:19], -0.5 op_sel_hi:[1,1,0]
	s_mov_b32 s43, s36
	v_pk_fma_f32 v[18:19], v[20:21], v[18:19], 1.0 op_sel_hi:[1,1,0]
	v_and_b32_e32 v21, 1, v9
	v_and_b32_e32 v20, 1, v2
	v_cmp_eq_u32_e32 vcc, 0, v21
	v_cmp_eq_u32_e64 s[4:5], 0, v20
	v_add_u32_e32 v9, 1, v9
	v_cndmask_b32_e32 v21, v18, v16, vcc
	v_cndmask_b32_e32 v18, v16, v18, vcc
	v_and_b32_e32 v16, 2, v2
	v_cndmask_b32_e64 v20, v19, v17, s[4:5]
	v_cmp_eq_u32_e32 vcc, 0, v16
	v_add_u32_e32 v2, 1, v2
	v_cndmask_b32_e64 v19, v17, v19, s[4:5]
	v_cndmask_b32_e64 v17, -v20, v20, vcc
	v_cmp_eq_u32_e32 vcc, 0, v22
	v_and_b32_e32 v2, 2, v2
	v_and_b32_e32 v9, 2, v9
	v_cndmask_b32_e64 v16, -v21, v21, vcc
	v_cmp_eq_u32_e32 vcc, 0, v2
	v_and_b32_e32 v21, 0xffff0000, v3
	v_lshlrev_b32_e32 v20, 16, v3
	s_waitcnt lgkmcnt(0)
	v_and_b32_e32 v3, 0xffff0000, v24
	v_lshlrev_b32_e32 v2, 16, v24
	v_cndmask_b32_e64 v19, -v19, v19, vcc
	v_cmp_eq_u32_e32 vcc, 0, v9
	v_pk_mul_f32 v[2:3], v[16:17], v[2:3]
	v_pk_mul_f32 v[16:17], v[8:9], s[38:39] op_sel_hi:[0,1]
	v_cndmask_b32_e64 v18, -v18, v18, vcc
	v_cndmask_b32_e64 v3, v3, -v3, s[0:1]
	v_cndmask_b32_e64 v2, v2, -v2, s[0:1]
	v_mul_f32_e32 v9, 0x3f22f983, v16
	v_pk_fma_f32 v[2:3], v[18:19], v[20:21], v[2:3]
	v_rndne_f32_e32 v18, v9
	v_mul_f32_e32 v9, 0x3f22f983, v17
	v_rndne_f32_e32 v19, v9
	v_pk_fma_f32 v[16:17], v[18:19], s[22:23], v[16:17] op_sel_hi:[1,0,1] neg_lo:[1,0,0] neg_hi:[1,0,0]
	v_cvt_i32_f32_e32 v9, v19
	v_pk_fma_f32 v[16:17], v[18:19], s[24:25], v[16:17] op_sel_hi:[1,0,1] neg_lo:[1,0,0] neg_hi:[1,0,0]
	v_cvt_i32_f32_e32 v24, v18
	v_pk_fma_f32 v[16:17], v[18:19], s[26:27], v[16:17] op_sel_hi:[1,0,1] neg_lo:[1,0,0] neg_hi:[1,0,0]
	v_cvt_pk_bf16_f32 v127, v2, v3
	v_pk_mul_f32 v[20:21], v[16:17], v[16:17]
	s_mov_b32 s38, s36
	v_pk_fma_f32 v[22:23], v[20:21], s[76:77], v[12:13] op_sel_hi:[1,0,0] neg_lo:[1,0,0] neg_hi:[1,0,0]
	v_pk_mul_f32 v[18:19], v[16:17], v[20:21]
	v_pk_fma_f32 v[22:23], v[20:21], v[22:23], s[78:79] op_sel_hi:[1,1,0]
	s_mov_b32 s39, s36
	v_pk_fma_f32 v[16:17], v[18:19], v[22:23], v[16:17]
	v_pk_fma_f32 v[18:19], v[20:21], s[80:81], v[14:15] op_sel_hi:[1,0,0]
	v_and_b32_e32 v23, 2, v24
	v_pk_fma_f32 v[18:19], v[20:21], v[18:19], s[82:83] op_sel_hi:[1,1,0]
	s_mov_b32 s44, s36
	v_pk_fma_f32 v[18:19], v[20:21], v[18:19], -0.5 op_sel_hi:[1,1,0]
	s_mov_b32 s45, s36
	v_pk_fma_f32 v[18:19], v[20:21], v[18:19], 1.0 op_sel_hi:[1,1,0]
	v_and_b32_e32 v21, 1, v24
	v_and_b32_e32 v20, 1, v9
	v_cmp_eq_u32_e32 vcc, 0, v21
	v_cmp_eq_u32_e64 s[4:5], 0, v20
	s_mov_b32 s46, s36
	v_cndmask_b32_e32 v21, v18, v16, vcc
	v_cndmask_b32_e32 v41, v16, v18, vcc
	v_and_b32_e32 v16, 2, v9
	v_cndmask_b32_e64 v20, v19, v17, s[4:5]
	v_cndmask_b32_e64 v22, v17, v19, s[4:5]
	v_cmp_eq_u32_e32 vcc, 0, v16
	v_lshl_add_u64 v[16:17], v[182:183], 0, s[90:91]
	s_add_i32 s4, s85, s6
	s_mov_b32 m0, s4
	s_nop 0
	global_load_lds_dwordx4 v[16:17], off
	v_lshl_add_u64 v[16:17], v[226:227], 0, s[92:93]
	s_add_i32 s4, s86, s6
	s_mov_b32 m0, s4
	s_nop 0
	global_load_lds_dwordx4 v[16:17], off
	s_waitcnt vmcnt(3) lgkmcnt(0)
	s_barrier
	ds_read_b128 v[16:19], v207
	ds_read_b128 v[34:37], v207 offset:512
	v_add_u32_e32 v9, 1, v9
	v_cndmask_b32_e64 v39, -v20, v20, vcc
	v_cmp_eq_u32_e32 vcc, 0, v23
	v_add_u32_e32 v20, 1, v24
	v_and_b32_e32 v9, 2, v9
	v_cndmask_b32_e64 v38, -v21, v21, vcc
	v_and_b32_e32 v42, 2, v20
	v_cmp_eq_u32_e32 vcc, 0, v9
	ds_read_b128 v[50:53], v207 offset:2048
	v_pk_mul_f32 v[8:9], v[8:9], s[40:41] op_sel_hi:[0,1]
	v_cndmask_b32_e64 v55, -v22, v22, vcc
	v_cmp_eq_u32_e32 vcc, 0, v42
	s_waitcnt lgkmcnt(2)
	v_mfma_f32_32x32x16_bf16 v[18:33], v[16:19], v[110:113], 0
	v_and_b32_e32 v17, 0xffff0000, v4
	v_cndmask_b32_e64 v54, -v41, v41, vcc
	v_and_b32_e32 v41, 0xffff0000, v40
	v_lshlrev_b32_e32 v40, 16, v40
	v_mul_f32_e64 v56, v38, v40
	v_mul_f32_e64 v57, v39, v41
	v_lshlrev_b32_e32 v16, 16, v4
	v_cndmask_b32_e64 v57, v57, -v57, s[0:1]
	v_cndmask_b32_e64 v56, v56, -v56, s[0:1]
	v_pk_fma_f32 v[16:17], v[54:55], v[16:17], v[56:57]
	ds_read_b128 v[54:57], v207 offset:2560
	s_waitcnt lgkmcnt(2)
	v_mfma_f32_32x32x16_bf16 v[34:49], v[34:37], v[110:113], 0
	v_mul_f32_e32 v4, 0x3f22f983, v8
	v_rndne_f32_e32 v58, v4
	v_mul_f32_e32 v4, 0x3f22f983, v9
	v_rndne_f32_e32 v59, v4
	v_fma_f32 v8, -v58, s22, v8
	v_fma_f32 v9, -v59, s22, v9
	v_cvt_i32_f32_e32 v4, v59
	v_pk_fma_f32 v[8:9], v[58:59], s[24:25], v[8:9] op_sel_hi:[1,0,1] neg_lo:[1,0,0] neg_hi:[1,0,0]
	s_waitcnt lgkmcnt(1)
	v_mfma_f32_32x32x16_bf16 v[18:33], v[50:53], v[106:109], v[18:33]
	v_fma_f32 v8, -v58, s26, v8
	v_fma_f32 v9, -v59, s26, v9
	ds_read_b128 v[50:53], v207 offset:4096
	v_mul_f32_e64 v60, v8, v8
	v_mul_f32_e64 v61, v9, v9
	v_cvt_i32_f32_e32 v58, v58
	v_pk_fma_f32 v[12:13], v[60:61], s[76:77], v[12:13] op_sel_hi:[1,0,0] neg_lo:[1,0,0] neg_hi:[1,0,0]
	v_cvt_pk_bf16_f32 v128, v16, v17
	v_pk_fma_f32 v[12:13], v[60:61], v[12:13], s[78:79] op_sel_hi:[1,1,0]
	s_waitcnt lgkmcnt(1)
	v_mfma_f32_32x32x16_bf16 v[34:49], v[54:57], v[106:109], v[34:49]
	v_mul_f32_e64 v54, v8, v60
	v_mul_f32_e64 v55, v9, v61
	s_mov_b32 s40, s36
	v_fma_f32 v8, v54, v12, v8
	v_fma_f32 v9, v55, v13, v9
	ds_read_b128 v[54:57], v207 offset:4608
	v_pk_fma_f32 v[12:13], v[60:61], s[80:81], v[14:15] op_sel_hi:[1,0,0]
	s_mov_b32 s41, s36
	v_pk_fma_f32 v[12:13], v[60:61], v[12:13], s[82:83] op_sel_hi:[1,1,0]
	s_waitcnt lgkmcnt(1)
	v_mfma_f32_32x32x16_bf16 v[18:33], v[50:53], v[102:105], v[18:33]
	v_fma_f32 v12, v60, v12, -0.5
	v_fma_f32 v13, v61, v13, -0.5
	v_and_b32_e32 v52, 1, v4
	v_and_b32_e32 v53, 1, v58
	v_fma_f32 v50, v60, v12, 1.0
	v_fma_f32 v51, v61, v13, 1.0
	ds_read_b128 v[12:15], v207 offset:6144
	v_cmp_eq_u32_e32 vcc, 0, v53
	v_cmp_eq_u32_e64 s[4:5], 0, v52
	s_waitcnt lgkmcnt(1)
	v_mfma_f32_32x32x16_bf16 v[34:49], v[54:57], v[102:105], v[34:49]
	v_cndmask_b32_e32 v54, v50, v8, vcc
	v_cndmask_b32_e64 v55, v51, v9, s[4:5]
	v_cndmask_b32_e32 v56, v8, v50, vcc
	v_cndmask_b32_e64 v57, v9, v51, s[4:5]
	ds_read_b128 v[50:53], v207 offset:6656
	v_and_b32_e32 v8, 2, v4
	v_cmp_eq_u32_e32 vcc, 0, v8
	s_waitcnt lgkmcnt(1)
	v_mfma_f32_32x32x16_bf16 v[18:33], v[12:15], v[98:101], v[18:33]
	v_and_b32_e32 v12, 2, v58
	v_cndmask_b32_e64 v9, -v55, v55, vcc
	v_cmp_eq_u32_e32 vcc, 0, v12
	ds_read_b128 v[12:15], v207 offset:8192
	v_add_u32_e32 v4, 1, v4
	v_cndmask_b32_e64 v8, -v54, v54, vcc
	v_and_b32_e32 v4, 2, v4
	s_waitcnt lgkmcnt(1)
	v_mfma_f32_32x32x16_bf16 v[34:49], v[50:53], v[98:101], v[34:49]
	v_add_u32_e32 v50, 1, v58
	v_and_b32_e32 v54, 2, v50
	ds_read_b128 v[50:53], v207 offset:8704
	v_cmp_eq_u32_e32 vcc, 0, v4
	v_lshlrev_b32_e32 v4, 16, v62
	s_mov_b64 s[4:5], 0x60000
	v_cndmask_b32_e64 v55, -v57, v57, vcc
	v_cmp_eq_u32_e32 vcc, 0, v54
	v_and_b32_e32 v57, 0xffff0000, v5
	s_waitcnt lgkmcnt(1)
	v_mfma_f32_32x32x16_bf16 v[18:33], v[12:15], v[114:117], v[18:33]
	v_cndmask_b32_e64 v54, -v56, v56, vcc
	v_lshlrev_b32_e32 v56, 16, v5
	v_and_b32_e32 v5, 0xffff0000, v62
	v_mul_f32_e64 v4, v8, v4
	v_mul_f32_e64 v5, v9, v5
	ds_read_b128 v[12:15], v207 offset:10240
	v_cndmask_b32_e64 v5, v5, -v5, s[0:1]
	v_cndmask_b32_e64 v4, v4, -v4, s[0:1]
	v_pk_fma_f32 v[4:5], v[54:55], v[56:57], v[4:5]
	s_waitcnt lgkmcnt(1)
	v_mfma_f32_32x32x16_bf16 v[34:49], v[50:53], v[114:117], v[34:49]
	v_cvt_pk_bf16_f32 v129, v4, v5
	ds_read_b128 v[2:5], v207 offset:10752
	s_mov_b32 s47, s36
	s_mov_b32 s48, s36
	s_mov_b32 s49, s36
	s_mov_b32 s50, s36
	s_mov_b32 s51, s36
	s_waitcnt lgkmcnt(1)
	v_mfma_f32_32x32x16_bf16 v[18:33], v[12:15], v[126:129], v[18:33]
	s_movk_i32 s6, 0x3000
	s_waitcnt lgkmcnt(0)
	v_mfma_f32_32x32x16_bf16 v[34:49], v[2:5], v[126:129], v[34:49]
	s_nop 15
	s_nop 7
	s_waitcnt vmcnt(0) lgkmcnt(0)
	s_barrier
	v_lshl_add_u64 v[2:3], v[182:183], 0, s[4:5]
	v_max3_f32 v50, v18, v19, v34
	s_mov_b32 m0, s87
	s_nop 0
	global_load_lds_dwordx4 v[2:3], off
	v_max3_f32 v51, v20, v21, v35
	s_mov_b64 s[4:5], 0x20080
	v_max3_f32 v50, v50, v36, v37
	v_max3_f32 v51, v51, v24, v25
	v_lshl_add_u64 v[2:3], v[10:11], 0, s[4:5]
	v_max3_f32 v50, v50, v22, v23
	s_add_i32 s4, s87, 0xc000
	s_mov_b32 m0, s4
	s_nop 0
	global_load_lds_dwordx4 v[2:3], off
	v_max3_f32 v50, v50, v38, v39
	v_max3_f32 v51, v51, v40, v41
	ds_read_b128 v[66:69], v207 offset:12288
	ds_read_b128 v[82:85], v207 offset:12800
	ds_read_b128 v[158:161], v207 offset:14336
	ds_read_b128 v[154:157], v207 offset:14848
	ds_read_b128 v[150:153], v207 offset:16384
	ds_read_b128 v[146:149], v207 offset:16896
	ds_read_b128 v[142:145], v207 offset:18432
	ds_read_b128 v[138:141], v207 offset:18944
	v_max3_f32 v50, v50, v26, v27
	v_max3_f32 v51, v51, v28, v29
	v_mov_b64_e32 v[2:3], s[36:37]
	v_max3_f32 v50, v50, v42, v43
	v_max3_f32 v51, v51, v44, v45
	s_lshl_b32 s4, s35, 2
	v_max3_f32 v50, v50, v30, v31
	v_max3_f32 v51, v51, v32, v33
	v_mov_b64_e32 v[4:5], s[38:39]
	v_max3_f32 v50, v50, v46, v47
	v_max3_f32 v51, v51, v48, v49
	v_mov_b64_e32 v[6:7], s[40:41]
	v_mov_b64_e32 v[8:9], s[42:43]
	v_mov_b64_e32 v[10:11], s[44:45]
	v_mov_b64_e32 v[12:13], s[46:47]
	v_mov_b64_e32 v[14:15], s[48:49]
	v_mov_b64_e32 v[16:17], s[50:51]
	v_max_f32_e32 v50, v50, v51
	s_add_i32 s37, s4, 0
	v_mov_b32_e32 v51, v50
	s_nop 1
	v_permlane32_swap_b32_e32 v50, v51
	s_add_i32 s37, s37, 0x12000
	v_max_f32_e32 v50, v50, v51
	s_add_u32 s4, s7, s70
	v_sub_f32_e32 v34, v34, v50
	v_sub_f32_e32 v35, v35, v50
	v_sub_f32_e32 v36, v36, v50
	v_sub_f32_e32 v37, v37, v50
	v_sub_f32_e32 v38, v38, v50
	v_sub_f32_e32 v39, v39, v50
	v_sub_f32_e32 v40, v40, v50
	v_sub_f32_e32 v41, v41, v50
	v_sub_f32_e32 v42, v42, v50
	v_sub_f32_e32 v43, v43, v50
	v_sub_f32_e32 v44, v44, v50
	v_sub_f32_e32 v45, v45, v50
	v_sub_f32_e32 v46, v46, v50
	v_sub_f32_e32 v47, v47, v50
	v_sub_f32_e32 v48, v48, v50
	v_sub_f32_e32 v49, v49, v50
	v_add_f32_e32 v224, v1, v50
	v_sub_f32_e32 v18, v18, v50
	v_sub_f32_e32 v19, v19, v50
	v_sub_f32_e32 v20, v20, v50
	v_sub_f32_e32 v21, v21, v50
	v_sub_f32_e32 v22, v22, v50
	v_sub_f32_e32 v23, v23, v50
	v_sub_f32_e32 v24, v24, v50
	v_sub_f32_e32 v25, v25, v50
	v_sub_f32_e32 v26, v26, v50
	v_sub_f32_e32 v27, v27, v50
	v_sub_f32_e32 v28, v28, v50
	v_sub_f32_e32 v29, v29, v50
	v_sub_f32_e32 v30, v30, v50
	v_sub_f32_e32 v31, v31, v50
	v_sub_f32_e32 v32, v32, v50
	v_sub_f32_e32 v33, v33, v50
	s_nop 0
	v_exp_f32_e32 v50, v18
	v_exp_f32_e32 v51, v19
	v_exp_f32_e32 v52, v20
	v_exp_f32_e32 v53, v21
	v_exp_f32_e32 v54, v22
	v_exp_f32_e32 v55, v23
	v_exp_f32_e32 v56, v24
	v_exp_f32_e32 v57, v25
	v_exp_f32_e32 v58, v26
	v_exp_f32_e32 v59, v27
	v_exp_f32_e32 v60, v28
	v_exp_f32_e32 v61, v29
	v_exp_f32_e32 v62, v30
	v_exp_f32_e32 v63, v31
	v_exp_f32_e32 v64, v32
	v_exp_f32_e32 v65, v33
	v_exp_f32_e32 v34, v34
	v_exp_f32_e32 v35, v35
	v_exp_f32_e32 v36, v36
	v_exp_f32_e32 v37, v37
	v_exp_f32_e32 v38, v38
	v_exp_f32_e32 v39, v39
	v_exp_f32_e32 v40, v40
	v_exp_f32_e32 v41, v41
	v_exp_f32_e32 v42, v42
	v_exp_f32_e32 v43, v43
	v_exp_f32_e32 v44, v44
	v_exp_f32_e32 v45, v45
	v_exp_f32_e32 v46, v46
	v_exp_f32_e32 v47, v47
	v_exp_f32_e32 v48, v48
	v_exp_f32_e32 v49, v49
	s_addc_u32 s5, 0, 0
	s_waitcnt vmcnt(2) lgkmcnt(0)
	s_barrier
	v_lshl_add_u64 v[18:19], s[4:5], 0, v[0:1]
	s_add_u32 s4, s7, s18
	v_lshl_add_u64 v[184:185], v[208:209], 0, v[18:19]
	s_addc_u32 s5, 0, 0
	v_mov_b64_e32 v[32:33], v[16:17]
	s_mov_b64 s[40:41], 0xfe0000
	s_mov_b64 s[38:39], 0xfc0000
	v_lshl_add_u32 v217, v191, 2, s37
	v_lshl_add_u64 v[186:187], v[210:211], 0, s[4:5]
	v_mov_b32_e32 v0, 0
	v_mov_b64_e32 v[30:31], v[14:15]
	v_mov_b64_e32 v[28:29], v[12:13]
	v_mov_b64_e32 v[26:27], v[10:11]
	v_mov_b64_e32 v[24:25], v[8:9]
	v_mov_b64_e32 v[22:23], v[6:7]
	v_mov_b64_e32 v[20:21], v[4:5]
	v_mov_b64_e32 v[18:19], v[2:3]
.LBB0_520:
	s_movk_i32 s4, 0xf000
	s_mov_b32 s5, -1
	v_lshl_add_u64 v[70:71], v[178:179], 0, s[4:5]
	s_add_i32 s4, s36, s84
	s_mov_b32 m0, s4
	s_nop 0
	global_load_lds_dwordx4 v[70:71], off
	v_add_u32_e32 v174, s36, v228
	ds_read_b64_tr_b16 v[170:171], v174 offset:36864
	ds_read_b64_tr_b16 v[172:173], v174 offset:37376
	v_add_f32_e32 v70, v50, v51
	v_add_f32_e32 v70, v52, v70
	v_add_f32_e32 v70, v53, v70
	v_add_f32_e32 v70, v54, v70
	v_add_f32_e32 v86, v55, v70
	s_waitcnt lgkmcnt(9)
	v_mfma_f32_32x32x16_bf16 v[66:81], v[66:69], v[110:113], 0
	v_cvt_pk_bf16_f32 v134, v50, v51
	v_cvt_pk_bf16_f32 v135, v52, v53
	ds_read_b64_tr_b16 v[166:167], v174 offset:40960
	ds_read_b64_tr_b16 v[168:169], v174 offset:41472
	v_add_f32_e32 v50, v56, v86
	v_add_f32_e32 v50, v57, v50
	v_add_f32_e32 v50, v58, v50
	v_add_f32_e32 v50, v59, v50
	v_cvt_pk_bf16_f32 v136, v54, v55
	v_cvt_pk_bf16_f32 v137, v56, v57
	s_waitcnt lgkmcnt(10)
	v_mfma_f32_32x32x16_bf16 v[82:97], v[82:85], v[110:113], 0
	ds_read_b64_tr_b16 v[162:163], v174 offset:37888
	ds_read_b64_tr_b16 v[164:165], v174 offset:38400
	s_waitcnt lgkmcnt(11)
	v_mfma_f32_32x32x16_bf16 v[66:81], v[158:161], v[106:109], v[66:81]
	v_add_f32_e32 v50, v60, v50
	v_add_f32_e32 v50, v61, v50
	v_add_f32_e32 v50, v62, v50
	v_add_f32_e32 v50, v63, v50
	v_cvt_pk_bf16_f32 v130, v58, v59
	v_cvt_pk_bf16_f32 v131, v60, v61
	ds_read_b64_tr_b16 v[158:159], v174 offset:41984
	ds_read_b64_tr_b16 v[160:161], v174 offset:42496
	v_add_f32_e32 v50, v64, v50
	v_add_f32_e32 v50, v65, v50
	v_add_f32_e32 v50, v34, v50
	v_add_f32_e32 v50, v35, v50
	v_cvt_pk_bf16_f32 v132, v62, v63
	v_cvt_pk_bf16_f32 v133, v64, v65
	s_waitcnt lgkmcnt(12)
	v_mfma_f32_32x32x16_bf16 v[82:97], v[154:157], v[106:109], v[82:97]
	ds_read_b64_tr_b16 v[154:155], v174 offset:38912
	ds_read_b64_tr_b16 v[156:157], v174 offset:39424
	s_waitcnt lgkmcnt(13)
	v_mfma_f32_32x32x16_bf16 v[66:81], v[150:153], v[102:105], v[66:81]
	v_add_f32_e32 v50, v36, v50
	v_add_f32_e32 v50, v37, v50
	v_add_f32_e32 v50, v38, v50
	v_add_f32_e32 v50, v39, v50
	v_cvt_pk_bf16_f32 v122, v34, v35
	v_cvt_pk_bf16_f32 v123, v36, v37
	ds_read_b64_tr_b16 v[150:151], v174 offset:43008
	ds_read_b64_tr_b16 v[152:153], v174 offset:43520
	v_add_f32_e32 v34, v40, v50
	v_add_f32_e32 v34, v41, v34
	v_add_f32_e32 v34, v42, v34
	v_add_f32_e32 v34, v43, v34
	v_cvt_pk_bf16_f32 v124, v38, v39
	v_cvt_pk_bf16_f32 v125, v40, v41
	s_waitcnt lgkmcnt(14)
	v_mfma_f32_32x32x16_bf16 v[82:97], v[146:149], v[102:105], v[82:97]
	ds_read_b64_tr_b16 v[146:147], v174 offset:39936
	ds_read_b64_tr_b16 v[148:149], v174 offset:40448
	s_waitcnt lgkmcnt(14)
	v_mfma_f32_32x32x16_bf16 v[66:81], v[142:145], v[98:101], v[66:81]
	v_add_f32_e32 v34, v44, v34
	v_add_f32_e32 v34, v45, v34
	v_add_f32_e32 v34, v46, v34
	v_add_f32_e32 v34, v47, v34
	v_cvt_pk_bf16_f32 v118, v42, v43
	v_cvt_pk_bf16_f32 v119, v44, v45
	ds_read_b64_tr_b16 v[142:143], v174 offset:44032
	ds_read_b64_tr_b16 v[144:145], v174 offset:44544
	v_add_f32_e32 v34, v48, v34
	v_add_f32_e32 v34, v49, v34
	v_mfma_f32_32x32x16_bf16 v[82:97], v[138:141], v[98:101], v[82:97]
	v_add_f32_e32 v138, 0, v34
	v_cvt_pk_bf16_f32 v120, v46, v47
	v_cvt_pk_bf16_f32 v121, v48, v49
	v_add_u32_e32 v38, s6, v207
	ds_read_b128 v[34:37], v38 offset:8192
	s_waitcnt lgkmcnt(0)
	v_mfma_f32_32x32x16_bf16 v[66:81], v[34:37], v[114:117], v[66:81]
	ds_read_b128 v[34:37], v38 offset:8704
	s_waitcnt lgkmcnt(0)
	v_mfma_f32_32x32x16_bf16 v[82:97], v[34:37], v[114:117], v[82:97]
	ds_read_b128 v[34:37], v38 offset:10240
	s_waitcnt lgkmcnt(0)
	v_mfma_f32_32x32x16_bf16 v[66:81], v[34:37], v[126:129], v[66:81]
	ds_read_b128 v[34:37], v38 offset:10752
	s_waitcnt lgkmcnt(0)
	v_mfma_f32_32x32x16_bf16 v[82:97], v[34:37], v[126:129], v[82:97]
	s_nop 8
	v_add_f32_e64 v50, v66, -v224
	v_add_f32_e64 v51, v67, -v224
	v_add_f32_e64 v52, v68, -v224
	v_add_f32_e64 v53, v69, -v224
	v_add_f32_e64 v54, v70, -v224
	v_add_f32_e64 v55, v71, -v224
	v_pk_add_f32 v[56:57], v[72:73], v[224:225] op_sel_hi:[1,0] neg_lo:[0,1] neg_hi:[0,1]
	v_pk_add_f32 v[58:59], v[74:75], v[224:225] op_sel_hi:[1,0] neg_lo:[0,1] neg_hi:[0,1]
	v_pk_add_f32 v[60:61], v[76:77], v[224:225] op_sel_hi:[1,0] neg_lo:[0,1] neg_hi:[0,1]
	v_pk_add_f32 v[62:63], v[78:79], v[224:225] op_sel_hi:[1,0] neg_lo:[0,1] neg_hi:[0,1]
	v_pk_add_f32 v[34:35], v[82:83], v[224:225] op_sel_hi:[1,0] neg_lo:[0,1] neg_hi:[0,1]
	v_pk_add_f32 v[36:37], v[84:85], v[224:225] op_sel_hi:[1,0] neg_lo:[0,1] neg_hi:[0,1]
	v_pk_add_f32 v[38:39], v[86:87], v[224:225] op_sel_hi:[1,0] neg_lo:[0,1] neg_hi:[0,1]
	v_pk_add_f32 v[40:41], v[88:89], v[224:225] op_sel_hi:[1,0] neg_lo:[0,1] neg_hi:[0,1]
	v_pk_add_f32 v[42:43], v[90:91], v[224:225] op_sel_hi:[1,0] neg_lo:[0,1] neg_hi:[0,1]
	v_pk_add_f32 v[44:45], v[92:93], v[224:225] op_sel_hi:[1,0] neg_lo:[0,1] neg_hi:[0,1]
	v_pk_add_f32 v[46:47], v[94:95], v[224:225] op_sel_hi:[1,0] neg_lo:[0,1] neg_hi:[0,1]
	v_pk_add_f32 v[64:65], v[80:81], v[224:225] op_sel_hi:[1,0] neg_lo:[0,1] neg_hi:[0,1]
	v_pk_add_f32 v[48:49], v[96:97], v[224:225] op_sel_hi:[1,0] neg_lo:[0,1] neg_hi:[0,1]
	s_add_i32 s4, s6, s87
	s_mov_b32 m0, s4
	s_nop 0
	global_load_lds_dwordx4 v[180:181], off
	v_lshl_add_u64 v[66:67], v[184:185], 0, s[20:21]
	s_add_i32 s4, s89, s71
	s_mov_b32 m0, s4
	s_nop 0
	global_load_lds_dwordx4 v[66:67], off
	v_max_f32_e32 v66, v50, v51
	v_max3_f32 v67, v52, v53, v35
	v_max3_f32 v66, v66, v34, v36
	v_max3_f32 v66, v66, v37, v54
	v_max3_f32 v67, v67, v56, v57
	v_max3_f32 v66, v66, v55, v38
	v_max3_f32 v67, v67, v40, v41
	v_max3_f32 v66, v66, v39, v58
	v_max3_f32 v67, v67, v60, v61
	v_max3_f32 v66, v66, v59, v42
	v_max3_f32 v67, v67, v44, v45
	v_max3_f32 v66, v66, v43, v62
	v_max3_f32 v67, v67, v64, v65
	v_max3_f32 v66, v66, v63, v46
	v_max3_f32 v67, v67, v48, v49
	v_max3_f32 v66, v66, v47, v67
	v_mov_b32_e32 v67, v66
	s_nop 1
	v_permlane32_swap_b32_e32 v66, v67
	v_max_f32_e32 v66, v66, v67
	v_cmp_lt_f32_e32 vcc, s27, v66
	s_cmp_lg_u64 vcc, 0
	v_add_f32_e32 v0, v0, v138
	s_cselect_b64 s[4:5], -1, 0
	s_cbranch_vccnz .LBB0_528

.LBB0_523:
	s_add_i32 s5, s6, s84
	s_mov_b32 m0, s5
	s_nop 0
	global_load_lds_dwordx4 v[178:179], off
	s_add_i32 s4, s89, 0x3000
	v_add_u32_e32 v189, s6, v228
	ds_read_b64_tr_b16 v[150:151], v189 offset:36864
	ds_read_b64_tr_b16 v[152:153], v189 offset:37376
	v_add_f32_e32 v70, v50, v51
	v_add_f32_e32 v70, v52, v70
	v_add_f32_e32 v70, v53, v70
	v_add_f32_e32 v70, v54, v70
	v_add_f32_e32 v86, v55, v70
	s_waitcnt lgkmcnt(9)
	v_mfma_f32_32x32x16_bf16 v[66:81], v[66:69], v[110:113], 0
	v_cvt_pk_bf16_f32 v134, v50, v51
	v_cvt_pk_bf16_f32 v135, v52, v53
	ds_read_b64_tr_b16 v[146:147], v189 offset:40960
	ds_read_b64_tr_b16 v[148:149], v189 offset:41472
	v_add_f32_e32 v50, v56, v86
	v_add_f32_e32 v50, v57, v50
	v_add_f32_e32 v50, v58, v50
	v_add_f32_e32 v50, v59, v50
	v_cvt_pk_bf16_f32 v136, v54, v55
	v_cvt_pk_bf16_f32 v137, v56, v57
	s_waitcnt lgkmcnt(10)
	v_mfma_f32_32x32x16_bf16 v[82:97], v[82:85], v[110:113], 0
	ds_read_b64_tr_b16 v[138:139], v189 offset:37888
	ds_read_b64_tr_b16 v[140:141], v189 offset:38400
	s_waitcnt lgkmcnt(11)
	v_mfma_f32_32x32x16_bf16 v[66:81], v[174:177], v[106:109], v[66:81]
	v_add_f32_e32 v50, v60, v50
	v_add_f32_e32 v50, v61, v50
	v_add_f32_e32 v50, v62, v50
	v_add_f32_e32 v50, v63, v50
	v_cvt_pk_bf16_f32 v130, v58, v59
	v_cvt_pk_bf16_f32 v131, v60, v61
	ds_read_b64_tr_b16 v[142:143], v189 offset:41984
	ds_read_b64_tr_b16 v[144:145], v189 offset:42496
	v_add_f32_e32 v50, v64, v50
	v_add_f32_e32 v50, v65, v50
	v_add_f32_e32 v50, v34, v50
	v_add_f32_e32 v50, v35, v50
	v_cvt_pk_bf16_f32 v132, v62, v63
	v_cvt_pk_bf16_f32 v133, v64, v65
	s_waitcnt lgkmcnt(12)
	v_mfma_f32_32x32x16_bf16 v[82:97], v[166:169], v[106:109], v[82:97]
	ds_read_b64_tr_b16 v[174:175], v189 offset:38912
	ds_read_b64_tr_b16 v[176:177], v189 offset:39424
	s_waitcnt lgkmcnt(13)
	v_mfma_f32_32x32x16_bf16 v[66:81], v[162:165], v[102:105], v[66:81]
	v_add_f32_e32 v50, v36, v50
	v_add_f32_e32 v50, v37, v50
	v_add_f32_e32 v50, v38, v50
	v_add_f32_e32 v50, v39, v50
	v_cvt_pk_bf16_f32 v122, v34, v35
	v_cvt_pk_bf16_f32 v123, v36, v37
	ds_read_b64_tr_b16 v[162:163], v189 offset:43008
	ds_read_b64_tr_b16 v[164:165], v189 offset:43520
	v_add_f32_e32 v34, v40, v50
	v_add_f32_e32 v34, v41, v34
	v_add_f32_e32 v34, v42, v34
	v_add_f32_e32 v34, v43, v34
	v_cvt_pk_bf16_f32 v124, v38, v39
	v_cvt_pk_bf16_f32 v125, v40, v41
	s_waitcnt lgkmcnt(14)
	v_mfma_f32_32x32x16_bf16 v[82:97], v[158:161], v[102:105], v[82:97]
	ds_read_b64_tr_b16 v[166:167], v189 offset:39936
	ds_read_b64_tr_b16 v[168:169], v189 offset:40448
	s_waitcnt lgkmcnt(14)
	v_mfma_f32_32x32x16_bf16 v[66:81], v[170:173], v[98:101], v[66:81]
	v_add_f32_e32 v34, v44, v34
	v_add_f32_e32 v34, v45, v34
	v_add_f32_e32 v34, v46, v34
	v_add_f32_e32 v34, v47, v34
	v_cvt_pk_bf16_f32 v118, v42, v43
	v_cvt_pk_bf16_f32 v119, v44, v45
	ds_read_b64_tr_b16 v[170:171], v189 offset:44032
	ds_read_b64_tr_b16 v[172:173], v189 offset:44544
	v_add_f32_e32 v34, v48, v34
	v_add_f32_e32 v34, v49, v34
	v_mfma_f32_32x32x16_bf16 v[82:97], v[154:157], v[98:101], v[82:97]
	v_add_f32_e32 v154, 0, v34
	v_cvt_pk_bf16_f32 v120, v46, v47
	v_cvt_pk_bf16_f32 v121, v48, v49
	ds_read_b128 v[34:37], v188 offset:8192
	s_cmpk_lg_i32 s89, 0x6000
	s_cselect_b32 s6, s4, 0
	s_waitcnt lgkmcnt(0)
	v_mfma_f32_32x32x16_bf16 v[66:81], v[34:37], v[114:117], v[66:81]
	ds_read_b128 v[34:37], v188 offset:8704
	s_waitcnt lgkmcnt(0)
	v_mfma_f32_32x32x16_bf16 v[82:97], v[34:37], v[114:117], v[82:97]
	ds_read_b128 v[34:37], v188 offset:10240
	s_waitcnt lgkmcnt(0)
	v_mfma_f32_32x32x16_bf16 v[66:81], v[34:37], v[126:129], v[66:81]
	ds_read_b128 v[34:37], v188 offset:10752
	s_waitcnt lgkmcnt(0)
	v_mfma_f32_32x32x16_bf16 v[82:97], v[34:37], v[126:129], v[82:97]
	s_nop 8
	v_add_f32_e64 v50, v66, -v224
	v_add_f32_e64 v51, v67, -v224
	v_add_f32_e64 v52, v68, -v224
	v_add_f32_e64 v53, v69, -v224
	v_add_f32_e64 v54, v70, -v224
	v_add_f32_e64 v55, v71, -v224
	v_pk_add_f32 v[56:57], v[72:73], v[224:225] op_sel_hi:[1,0] neg_lo:[0,1] neg_hi:[0,1]
	v_pk_add_f32 v[58:59], v[74:75], v[224:225] op_sel_hi:[1,0] neg_lo:[0,1] neg_hi:[0,1]
	v_pk_add_f32 v[60:61], v[76:77], v[224:225] op_sel_hi:[1,0] neg_lo:[0,1] neg_hi:[0,1]
	v_pk_add_f32 v[62:63], v[78:79], v[224:225] op_sel_hi:[1,0] neg_lo:[0,1] neg_hi:[0,1]
	v_pk_add_f32 v[34:35], v[82:83], v[224:225] op_sel_hi:[1,0] neg_lo:[0,1] neg_hi:[0,1]
	v_pk_add_f32 v[36:37], v[84:85], v[224:225] op_sel_hi:[1,0] neg_lo:[0,1] neg_hi:[0,1]
	v_pk_add_f32 v[38:39], v[86:87], v[224:225] op_sel_hi:[1,0] neg_lo:[0,1] neg_hi:[0,1]
	v_pk_add_f32 v[40:41], v[88:89], v[224:225] op_sel_hi:[1,0] neg_lo:[0,1] neg_hi:[0,1]
	v_pk_add_f32 v[42:43], v[90:91], v[224:225] op_sel_hi:[1,0] neg_lo:[0,1] neg_hi:[0,1]
	v_pk_add_f32 v[44:45], v[92:93], v[224:225] op_sel_hi:[1,0] neg_lo:[0,1] neg_hi:[0,1]
	v_pk_add_f32 v[46:47], v[94:95], v[224:225] op_sel_hi:[1,0] neg_lo:[0,1] neg_hi:[0,1]
	v_pk_add_f32 v[64:65], v[80:81], v[224:225] op_sel_hi:[1,0] neg_lo:[0,1] neg_hi:[0,1]
	v_pk_add_f32 v[48:49], v[96:97], v[224:225] op_sel_hi:[1,0] neg_lo:[0,1] neg_hi:[0,1]
	v_lshl_add_u64 v[66:67], v[186:187], 0, s[96:97]
	s_add_i32 s4, s89, s87
	s_mov_b32 m0, s4
	s_nop 0
	global_load_lds_dwordx4 v[66:67], off
	v_max_f32_e32 v66, v50, v51
	v_max3_f32 v67, v52, v53, v35
	v_max3_f32 v66, v66, v34, v36
	v_max3_f32 v66, v66, v37, v54
	v_max3_f32 v67, v67, v56, v57
	v_max3_f32 v66, v66, v55, v38
	v_max3_f32 v67, v67, v40, v41
	v_max3_f32 v66, v66, v39, v58
	v_max3_f32 v67, v67, v60, v61
	v_max3_f32 v66, v66, v59, v42
	v_max3_f32 v67, v67, v44, v45
	v_max3_f32 v66, v66, v43, v62
	v_max3_f32 v67, v67, v64, v65
	v_max3_f32 v66, v66, v63, v46
	v_max3_f32 v67, v67, v48, v49
	v_max3_f32 v66, v66, v47, v67
	v_mov_b32_e32 v67, v66
	s_nop 1
	v_permlane32_swap_b32_e32 v66, v67
	v_max_f32_e32 v66, v66, v67
	v_lshl_add_u64 v[184:185], v[184:185], 0, s[90:91]
	s_add_i32 s4, s6, s71
	s_mov_b32 m0, s4
	s_nop 0
	global_load_lds_dwordx4 v[184:185], off
	v_cmp_lt_f32_e32 vcc, s27, v66
	s_cmp_lg_u64 vcc, 0
	v_add_f32_e32 v0, v0, v154
	s_cselect_b64 s[4:5], -1, 0
	s_cbranch_vccnz .LBB0_531

.LBB0_534:
	s_mov_b64 s[4:5], 0x7d000
	s_cmp_lg_u32 0, -1
	v_lshl_add_u64 v[70:71], v[226:227], 0, s[4:5]
	s_cselect_b32 s4, 0, 0
	s_add_i32 s5, s4, s86
	s_addk_i32 s5, 0x6000
	s_mov_b32 m0, s5
	s_nop 0
	global_load_lds_dwordx4 v[70:71], off
	ds_read_b64_tr_b16 v[170:171], v228 offset:61440
	ds_read_b64_tr_b16 v[172:173], v228 offset:61952
	v_add_f32_e32 v70, v50, v51
	v_add_f32_e32 v70, v52, v70
	v_add_f32_e32 v70, v53, v70
	v_add_f32_e32 v70, v54, v70
	v_add_f32_e32 v86, v55, v70
	v_cvt_pk_bf16_f32 v134, v50, v51
	v_cvt_pk_bf16_f32 v135, v52, v53
	s_waitcnt lgkmcnt(9)
	v_mfma_f32_32x32x16_bf16 v[66:81], v[66:69], v[110:113], 0
	ds_read_b64_tr_b16 v[166:167], v229 offset:28672
	ds_read_b64_tr_b16 v[168:169], v229 offset:29184
	v_add_f32_e32 v50, v56, v86
	v_add_f32_e32 v50, v57, v50
	v_add_f32_e32 v50, v58, v50
	v_add_f32_e32 v50, v59, v50
	v_cvt_pk_bf16_f32 v136, v54, v55
	v_cvt_pk_bf16_f32 v137, v56, v57
	s_waitcnt lgkmcnt(10)
	v_mfma_f32_32x32x16_bf16 v[82:97], v[82:85], v[110:113], 0
	ds_read_b64_tr_b16 v[162:163], v228 offset:62464
	ds_read_b64_tr_b16 v[164:165], v228 offset:62976
	v_add_f32_e32 v50, v60, v50
	v_add_f32_e32 v50, v61, v50
	v_add_f32_e32 v50, v62, v50
	v_add_f32_e32 v50, v63, v50
	v_cvt_pk_bf16_f32 v130, v58, v59
	v_cvt_pk_bf16_f32 v131, v60, v61
	s_waitcnt lgkmcnt(11)
	v_mfma_f32_32x32x16_bf16 v[66:81], v[158:161], v[106:109], v[66:81]
	ds_read_b64_tr_b16 v[158:159], v229 offset:29696
	ds_read_b64_tr_b16 v[160:161], v229 offset:30208
	v_add_f32_e32 v50, v64, v50
	v_add_f32_e32 v50, v65, v50
	v_add_f32_e32 v50, v34, v50
	v_add_f32_e32 v50, v35, v50
	v_cvt_pk_bf16_f32 v132, v62, v63
	v_cvt_pk_bf16_f32 v133, v64, v65
	s_waitcnt lgkmcnt(12)
	v_mfma_f32_32x32x16_bf16 v[82:97], v[154:157], v[106:109], v[82:97]
	ds_read_b64_tr_b16 v[154:155], v228 offset:63488
	ds_read_b64_tr_b16 v[156:157], v228 offset:64000
	v_add_f32_e32 v50, v36, v50
	v_add_f32_e32 v50, v37, v50
	v_add_f32_e32 v50, v38, v50
	v_add_f32_e32 v50, v39, v50
	v_cvt_pk_bf16_f32 v122, v34, v35
	v_cvt_pk_bf16_f32 v123, v36, v37
	s_waitcnt lgkmcnt(13)
	v_mfma_f32_32x32x16_bf16 v[66:81], v[150:153], v[102:105], v[66:81]
	ds_read_b64_tr_b16 v[150:151], v229 offset:30720
	ds_read_b64_tr_b16 v[152:153], v229 offset:31232
	v_add_f32_e32 v34, v40, v50
	v_add_f32_e32 v34, v41, v34
	v_add_f32_e32 v34, v42, v34
	v_add_f32_e32 v34, v43, v34
	v_cvt_pk_bf16_f32 v124, v38, v39
	v_cvt_pk_bf16_f32 v125, v40, v41
	s_waitcnt lgkmcnt(14)
	v_mfma_f32_32x32x16_bf16 v[82:97], v[146:149], v[102:105], v[82:97]
	ds_read_b64_tr_b16 v[146:147], v228 offset:64512
	ds_read_b64_tr_b16 v[148:149], v228 offset:65024
	v_add_f32_e32 v34, v44, v34
	v_add_f32_e32 v34, v45, v34
	v_add_f32_e32 v34, v46, v34
	v_add_f32_e32 v34, v47, v34
	v_cvt_pk_bf16_f32 v118, v42, v43
	v_cvt_pk_bf16_f32 v119, v44, v45
	s_waitcnt lgkmcnt(14)
	v_mfma_f32_32x32x16_bf16 v[66:81], v[142:145], v[98:101], v[66:81]
	ds_read_b64_tr_b16 v[142:143], v229 offset:31744
	ds_read_b64_tr_b16 v[144:145], v229 offset:32256
	v_add_f32_e32 v34, v48, v34
	v_add_f32_e32 v34, v49, v34
	v_mfma_f32_32x32x16_bf16 v[82:97], v[138:141], v[98:101], v[82:97]
	v_add_f32_e32 v138, 0, v34
	v_cvt_pk_bf16_f32 v120, v46, v47
	v_cvt_pk_bf16_f32 v121, v48, v49
	ds_read_b128 v[34:37], v207 offset:8192
	v_add_f32_e32 v184, v0, v138
	s_waitcnt lgkmcnt(0)
	v_mfma_f32_32x32x16_bf16 v[66:81], v[34:37], v[114:117], v[66:81]
	ds_read_b128 v[34:37], v207 offset:8704
	s_waitcnt lgkmcnt(0)
	v_mfma_f32_32x32x16_bf16 v[82:97], v[34:37], v[114:117], v[82:97]
	ds_read_b128 v[34:37], v207 offset:10240
	s_waitcnt lgkmcnt(0)
	v_mfma_f32_32x32x16_bf16 v[66:81], v[34:37], v[126:129], v[66:81]
	ds_read_b128 v[34:37], v207 offset:10752
	s_waitcnt lgkmcnt(0)
	v_mfma_f32_32x32x16_bf16 v[82:97], v[34:37], v[126:129], v[82:97]
	s_nop 8
	v_add_f32_e64 v50, v66, -v224
	v_add_f32_e64 v51, v67, -v224
	v_add_f32_e64 v52, v68, -v224
	v_add_f32_e64 v53, v69, -v224
	v_add_f32_e64 v54, v70, -v224
	v_add_f32_e64 v55, v71, -v224
	v_pk_add_f32 v[56:57], v[72:73], v[224:225] op_sel_hi:[1,0] neg_lo:[0,1] neg_hi:[0,1]
	v_pk_add_f32 v[58:59], v[74:75], v[224:225] op_sel_hi:[1,0] neg_lo:[0,1] neg_hi:[0,1]
	v_pk_add_f32 v[60:61], v[76:77], v[224:225] op_sel_hi:[1,0] neg_lo:[0,1] neg_hi:[0,1]
	v_pk_add_f32 v[62:63], v[78:79], v[224:225] op_sel_hi:[1,0] neg_lo:[0,1] neg_hi:[0,1]
	v_pk_add_f32 v[34:35], v[82:83], v[224:225] op_sel_hi:[1,0] neg_lo:[0,1] neg_hi:[0,1]
	v_pk_add_f32 v[36:37], v[84:85], v[224:225] op_sel_hi:[1,0] neg_lo:[0,1] neg_hi:[0,1]
	v_pk_add_f32 v[38:39], v[86:87], v[224:225] op_sel_hi:[1,0] neg_lo:[0,1] neg_hi:[0,1]
	v_pk_add_f32 v[40:41], v[88:89], v[224:225] op_sel_hi:[1,0] neg_lo:[0,1] neg_hi:[0,1]
	v_pk_add_f32 v[42:43], v[90:91], v[224:225] op_sel_hi:[1,0] neg_lo:[0,1] neg_hi:[0,1]
	v_pk_add_f32 v[44:45], v[92:93], v[224:225] op_sel_hi:[1,0] neg_lo:[0,1] neg_hi:[0,1]
	v_pk_add_f32 v[46:47], v[94:95], v[224:225] op_sel_hi:[1,0] neg_lo:[0,1] neg_hi:[0,1]
	v_pk_add_f32 v[64:65], v[80:81], v[224:225] op_sel_hi:[1,0] neg_lo:[0,1] neg_hi:[0,1]
	v_pk_add_f32 v[48:49], v[96:97], v[224:225] op_sel_hi:[1,0] neg_lo:[0,1] neg_hi:[0,1]
	v_lshl_add_u64 v[66:67], v[182:183], 0, s[38:39]
	s_mov_b64 s[6:7], 0xf80000
	s_mov_b32 m0, s87
	s_nop 0
	global_load_lds_dwordx4 v[66:67], off
	v_lshl_add_u64 v[66:67], v[222:223], 0, s[6:7]
	s_add_i32 s4, s4, s85
	v_max_f32_e32 v0, v50, v51
	s_add_i32 s36, s4, 0xc000
	s_mov_b32 m0, s36
	s_nop 0
	global_load_lds_dwordx4 v[66:67], off
	v_max3_f32 v66, v52, v53, v35
	v_max3_f32 v0, v0, v34, v36
	v_max3_f32 v0, v0, v37, v54
	v_max3_f32 v66, v66, v56, v57
	v_max3_f32 v0, v0, v55, v38
	v_max3_f32 v66, v66, v40, v41
	v_max3_f32 v0, v0, v39, v58
	v_max3_f32 v66, v66, v60, v61
	v_max3_f32 v0, v0, v59, v42
	v_max3_f32 v66, v66, v44, v45
	v_max3_f32 v0, v0, v43, v62
	v_max3_f32 v66, v66, v64, v65
	v_max3_f32 v0, v0, v63, v46
	v_max3_f32 v66, v66, v48, v49
	v_max3_f32 v0, v0, v47, v66
	v_mov_b32_e32 v66, v0
	s_nop 1
	v_permlane32_swap_b32_e32 v0, v66
	v_max_f32_e32 v0, v0, v66
	v_cmp_lt_f32_e32 vcc, s27, v0
	s_cmp_lg_u64 vcc, 0
	s_cselect_b64 s[4:5], -1, 0
	s_cbranch_vccnz .LBB0_584

.LBB0_537:
	s_mov_b64 s[4:5], 0x7e000
	v_lshl_add_u64 v[70:71], v[226:227], 0, s[4:5]
	s_mov_b32 m0, s84
	s_nop 0
	global_load_lds_dwordx4 v[70:71], off
	ds_read_b64_tr_b16 v[166:167], v228 offset:36864
	ds_read_b64_tr_b16 v[168:169], v228 offset:37376
	v_add_f32_e32 v70, v50, v51
	v_add_f32_e32 v70, v52, v70
	v_add_f32_e32 v70, v53, v70
	v_add_f32_e32 v70, v54, v70
	v_add_f32_e32 v86, v55, v70
	s_waitcnt lgkmcnt(9)
	v_mfma_f32_32x32x16_bf16 v[66:81], v[66:69], v[110:113], 0
	v_cvt_pk_bf16_f32 v134, v50, v51
	v_cvt_pk_bf16_f32 v135, v52, v53
	ds_read_b64_tr_b16 v[158:159], v228 offset:40960
	ds_read_b64_tr_b16 v[160:161], v228 offset:41472
	v_add_f32_e32 v50, v56, v86
	v_add_f32_e32 v50, v57, v50
	v_add_f32_e32 v50, v58, v50
	v_add_f32_e32 v50, v59, v50
	v_cvt_pk_bf16_f32 v136, v54, v55
	v_cvt_pk_bf16_f32 v137, v56, v57
	s_waitcnt lgkmcnt(10)
	v_mfma_f32_32x32x16_bf16 v[82:97], v[82:85], v[110:113], 0
	ds_read_b64_tr_b16 v[146:147], v228 offset:37888
	ds_read_b64_tr_b16 v[148:149], v228 offset:38400
	s_waitcnt lgkmcnt(11)
	v_mfma_f32_32x32x16_bf16 v[66:81], v[178:181], v[106:109], v[66:81]
	v_add_f32_e32 v50, v60, v50
	v_add_f32_e32 v50, v61, v50
	v_add_f32_e32 v50, v62, v50
	v_add_f32_e32 v50, v63, v50
	v_cvt_pk_bf16_f32 v130, v58, v59
	v_cvt_pk_bf16_f32 v131, v60, v61
	ds_read_b64_tr_b16 v[150:151], v228 offset:41984
	ds_read_b64_tr_b16 v[152:153], v228 offset:42496
	v_add_f32_e32 v50, v64, v50
	v_add_f32_e32 v50, v65, v50
	v_add_f32_e32 v50, v34, v50
	v_add_f32_e32 v50, v35, v50
	v_cvt_pk_bf16_f32 v132, v62, v63
	v_cvt_pk_bf16_f32 v133, v64, v65
	s_waitcnt lgkmcnt(12)
	v_mfma_f32_32x32x16_bf16 v[82:97], v[162:165], v[106:109], v[82:97]
	ds_read_b64_tr_b16 v[162:163], v228 offset:38912
	ds_read_b64_tr_b16 v[164:165], v228 offset:39424
	s_waitcnt lgkmcnt(13)
	v_mfma_f32_32x32x16_bf16 v[66:81], v[138:141], v[102:105], v[66:81]
	v_add_f32_e32 v50, v36, v50
	v_add_f32_e32 v50, v37, v50
	v_add_f32_e32 v50, v38, v50
	v_add_f32_e32 v50, v39, v50
	v_cvt_pk_bf16_f32 v122, v34, v35
	v_cvt_pk_bf16_f32 v123, v36, v37
	ds_read_b64_tr_b16 v[138:139], v228 offset:43008
	ds_read_b64_tr_b16 v[140:141], v228 offset:43520
	v_add_f32_e32 v34, v40, v50
	v_add_f32_e32 v34, v41, v34
	v_add_f32_e32 v34, v42, v34
	v_add_f32_e32 v34, v43, v34
	v_cvt_pk_bf16_f32 v124, v38, v39
	v_cvt_pk_bf16_f32 v125, v40, v41
	s_waitcnt lgkmcnt(14)
	v_mfma_f32_32x32x16_bf16 v[82:97], v[174:177], v[102:105], v[82:97]
	ds_read_b64_tr_b16 v[142:143], v228 offset:39936
	ds_read_b64_tr_b16 v[144:145], v228 offset:40448
	s_waitcnt lgkmcnt(14)
	v_mfma_f32_32x32x16_bf16 v[66:81], v[154:157], v[98:101], v[66:81]
	v_add_f32_e32 v34, v44, v34
	v_add_f32_e32 v34, v45, v34
	v_add_f32_e32 v34, v46, v34
	v_add_f32_e32 v34, v47, v34
	v_cvt_pk_bf16_f32 v118, v42, v43
	v_cvt_pk_bf16_f32 v119, v44, v45
	ds_read_b64_tr_b16 v[154:155], v228 offset:44032
	ds_read_b64_tr_b16 v[156:157], v228 offset:44544
	v_add_f32_e32 v34, v48, v34
	v_add_f32_e32 v34, v49, v34
	v_mfma_f32_32x32x16_bf16 v[82:97], v[170:173], v[98:101], v[82:97]
	v_add_f32_e32 v170, 0, v34
	v_cvt_pk_bf16_f32 v120, v46, v47
	v_cvt_pk_bf16_f32 v121, v48, v49
	ds_read_b128 v[34:37], v207 offset:20480
	v_add_f32_e32 v219, v184, v170
	s_waitcnt lgkmcnt(0)
	v_mfma_f32_32x32x16_bf16 v[66:81], v[34:37], v[114:117], v[66:81]
	ds_read_b128 v[34:37], v207 offset:20992
	s_waitcnt lgkmcnt(0)
	v_mfma_f32_32x32x16_bf16 v[82:97], v[34:37], v[114:117], v[82:97]
	ds_read_b128 v[34:37], v207 offset:22528
	s_waitcnt lgkmcnt(0)
	v_mfma_f32_32x32x16_bf16 v[66:81], v[34:37], v[126:129], v[66:81]
	ds_read_b128 v[34:37], v207 offset:23040
	s_waitcnt lgkmcnt(0)
	v_mfma_f32_32x32x16_bf16 v[82:97], v[34:37], v[126:129], v[82:97]
	s_nop 8
	v_add_f32_e64 v50, v66, -v224
	v_add_f32_e64 v51, v67, -v224
	v_add_f32_e64 v52, v68, -v224
	v_add_f32_e64 v53, v69, -v224
	v_add_f32_e64 v54, v70, -v224
	v_add_f32_e64 v55, v71, -v224
	v_pk_add_f32 v[56:57], v[72:73], v[224:225] op_sel_hi:[1,0] neg_lo:[0,1] neg_hi:[0,1]
	v_pk_add_f32 v[58:59], v[74:75], v[224:225] op_sel_hi:[1,0] neg_lo:[0,1] neg_hi:[0,1]
	v_pk_add_f32 v[60:61], v[76:77], v[224:225] op_sel_hi:[1,0] neg_lo:[0,1] neg_hi:[0,1]
	v_pk_add_f32 v[62:63], v[78:79], v[224:225] op_sel_hi:[1,0] neg_lo:[0,1] neg_hi:[0,1]
	v_pk_add_f32 v[34:35], v[82:83], v[224:225] op_sel_hi:[1,0] neg_lo:[0,1] neg_hi:[0,1]
	v_pk_add_f32 v[36:37], v[84:85], v[224:225] op_sel_hi:[1,0] neg_lo:[0,1] neg_hi:[0,1]
	v_pk_add_f32 v[38:39], v[86:87], v[224:225] op_sel_hi:[1,0] neg_lo:[0,1] neg_hi:[0,1]
	v_pk_add_f32 v[40:41], v[88:89], v[224:225] op_sel_hi:[1,0] neg_lo:[0,1] neg_hi:[0,1]
	v_pk_add_f32 v[42:43], v[90:91], v[224:225] op_sel_hi:[1,0] neg_lo:[0,1] neg_hi:[0,1]
	v_pk_add_f32 v[44:45], v[92:93], v[224:225] op_sel_hi:[1,0] neg_lo:[0,1] neg_hi:[0,1]
	v_pk_add_f32 v[46:47], v[94:95], v[224:225] op_sel_hi:[1,0] neg_lo:[0,1] neg_hi:[0,1]
	v_pk_add_f32 v[64:65], v[80:81], v[224:225] op_sel_hi:[1,0] neg_lo:[0,1] neg_hi:[0,1]
	v_pk_add_f32 v[48:49], v[96:97], v[224:225] op_sel_hi:[1,0] neg_lo:[0,1] neg_hi:[0,1]
	s_cmp_lg_u32 0, -1
	s_cselect_b32 s4, 0, 0
	s_add_i32 s6, s4, s85
	v_lshl_add_u64 v[66:67], v[182:183], 0, s[40:41]
	s_add_i32 s4, s6, 0x3000
	s_mov_b32 m0, s4
	s_nop 0
	global_load_lds_dwordx4 v[66:67], off
	s_mov_b64 s[4:5], 0xfa0000
	v_lshl_add_u64 v[66:67], v[222:223], 0, s[4:5]
	s_add_i32 s6, s6, 0xf000
	s_mov_b32 m0, s6
	s_nop 0
	global_load_lds_dwordx4 v[66:67], off
	v_max_f32_e32 v66, v50, v51
	v_max3_f32 v67, v52, v53, v35
	v_max3_f32 v66, v66, v34, v36
	v_max3_f32 v66, v66, v37, v54
	v_max3_f32 v67, v67, v56, v57
	v_max3_f32 v66, v66, v55, v38
	v_max3_f32 v67, v67, v40, v41
	v_max3_f32 v66, v66, v39, v58
	v_max3_f32 v67, v67, v60, v61
	v_max3_f32 v66, v66, v59, v42
	v_max3_f32 v67, v67, v44, v45
	v_max3_f32 v66, v66, v43, v62
	v_max3_f32 v67, v67, v64, v65
	v_max3_f32 v66, v66, v63, v46
	v_max3_f32 v67, v67, v48, v49
	v_max3_f32 v66, v66, v47, v67
	v_mov_b32_e32 v67, v66
	s_nop 1
	v_permlane32_swap_b32_e32 v66, v67
	v_max_f32_e32 v66, v66, v67
	v_cmp_lt_f32_e32 vcc, s27, v66
	s_cmp_lg_u64 vcc, 0
	s_cselect_b64 s[4:5], -1, 0
	s_cbranch_vccnz .LBB0_587

.LBB0_540:
	s_mov_b64 s[4:5], 0x7f000
	s_cmp_lg_u32 0, -1
	v_lshl_add_u64 v[70:71], v[226:227], 0, s[4:5]
	s_cselect_b32 s4, 0, 0
	s_add_i32 s4, s4, s86
	s_addk_i32 s4, 0x3000
	s_mov_b32 m0, s4
	s_nop 0
	global_load_lds_dwordx4 v[70:71], off
	ds_read_b64_tr_b16 v[166:167], v228 offset:49152
	ds_read_b64_tr_b16 v[168:169], v228 offset:49664
	v_add_f32_e32 v70, v50, v51
	v_add_f32_e32 v70, v52, v70
	v_add_f32_e32 v70, v53, v70
	v_add_f32_e32 v70, v54, v70
	v_add_f32_e32 v86, v55, v70
	s_waitcnt lgkmcnt(9)
	v_mfma_f32_32x32x16_bf16 v[66:81], v[66:69], v[110:113], 0
	v_cvt_pk_bf16_f32 v134, v50, v51
	v_cvt_pk_bf16_f32 v135, v52, v53
	ds_read_b64_tr_b16 v[154:155], v228 offset:53248
	ds_read_b64_tr_b16 v[156:157], v228 offset:53760
	v_add_f32_e32 v50, v56, v86
	v_add_f32_e32 v50, v57, v50
	v_add_f32_e32 v50, v58, v50
	v_add_f32_e32 v50, v59, v50
	v_cvt_pk_bf16_f32 v136, v54, v55
	v_cvt_pk_bf16_f32 v137, v56, v57
	s_waitcnt lgkmcnt(10)
	v_mfma_f32_32x32x16_bf16 v[82:97], v[82:85], v[110:113], 0
	ds_read_b64_tr_b16 v[146:147], v228 offset:50176
	ds_read_b64_tr_b16 v[148:149], v228 offset:50688
	s_waitcnt lgkmcnt(11)
	v_mfma_f32_32x32x16_bf16 v[66:81], v[186:189], v[106:109], v[66:81]
	v_add_f32_e32 v50, v60, v50
	v_add_f32_e32 v50, v61, v50
	v_add_f32_e32 v50, v62, v50
	v_add_f32_e32 v50, v63, v50
	v_cvt_pk_bf16_f32 v130, v58, v59
	v_cvt_pk_bf16_f32 v131, v60, v61
	ds_read_b64_tr_b16 v[150:151], v228 offset:54272
	ds_read_b64_tr_b16 v[152:153], v228 offset:54784
	v_add_f32_e32 v50, v64, v50
	v_add_f32_e32 v50, v65, v50
	v_add_f32_e32 v50, v34, v50
	v_add_f32_e32 v50, v35, v50
	v_cvt_pk_bf16_f32 v132, v62, v63
	v_cvt_pk_bf16_f32 v133, v64, v65
	s_waitcnt lgkmcnt(12)
	v_mfma_f32_32x32x16_bf16 v[82:97], v[182:185], v[106:109], v[82:97]
	ds_read_b64_tr_b16 v[162:163], v228 offset:51200
	ds_read_b64_tr_b16 v[164:165], v228 offset:51712
	s_waitcnt lgkmcnt(13)
	v_mfma_f32_32x32x16_bf16 v[66:81], v[178:181], v[102:105], v[66:81]
	v_add_f32_e32 v50, v36, v50
	v_add_f32_e32 v50, v37, v50
	v_add_f32_e32 v50, v38, v50
	v_add_f32_e32 v50, v39, v50
	v_cvt_pk_bf16_f32 v122, v34, v35
	v_cvt_pk_bf16_f32 v123, v36, v37
	ds_read_b64_tr_b16 v[138:139], v228 offset:55296
	ds_read_b64_tr_b16 v[140:141], v228 offset:55808
	v_add_f32_e32 v34, v40, v50
	v_add_f32_e32 v34, v41, v34
	v_add_f32_e32 v34, v42, v34
	v_add_f32_e32 v34, v43, v34
	v_cvt_pk_bf16_f32 v124, v38, v39
	v_cvt_pk_bf16_f32 v125, v40, v41
	s_waitcnt lgkmcnt(14)
	v_mfma_f32_32x32x16_bf16 v[82:97], v[158:161], v[102:105], v[82:97]
	ds_read_b64_tr_b16 v[142:143], v228 offset:52224
	ds_read_b64_tr_b16 v[144:145], v228 offset:52736
	s_waitcnt lgkmcnt(14)
	v_mfma_f32_32x32x16_bf16 v[66:81], v[174:177], v[98:101], v[66:81]
	v_add_f32_e32 v34, v44, v34
	v_add_f32_e32 v34, v45, v34
	v_add_f32_e32 v34, v46, v34
	v_add_f32_e32 v34, v47, v34
	v_cvt_pk_bf16_f32 v118, v42, v43
	v_cvt_pk_bf16_f32 v119, v44, v45
	ds_read_b64_tr_b16 v[158:159], v228 offset:56320
	ds_read_b64_tr_b16 v[160:161], v228 offset:56832
	v_add_f32_e32 v34, v48, v34
	v_add_f32_e32 v34, v49, v34
	v_mfma_f32_32x32x16_bf16 v[82:97], v[170:173], v[98:101], v[82:97]
	v_add_f32_e32 v170, 0, v34
	v_cvt_pk_bf16_f32 v120, v46, v47
	v_cvt_pk_bf16_f32 v121, v48, v49
	ds_read_b128 v[34:37], v207 offset:32768
	v_add_f32_e32 v219, v219, v170
	s_waitcnt lgkmcnt(0)
	v_mfma_f32_32x32x16_bf16 v[66:81], v[34:37], v[114:117], v[66:81]
	ds_read_b128 v[34:37], v207 offset:33280
	s_waitcnt lgkmcnt(0)
	v_mfma_f32_32x32x16_bf16 v[82:97], v[34:37], v[114:117], v[82:97]
	ds_read_b128 v[34:37], v207 offset:34816
	s_waitcnt lgkmcnt(0)
	v_mfma_f32_32x32x16_bf16 v[66:81], v[34:37], v[126:129], v[66:81]
	ds_read_b128 v[34:37], v207 offset:35328
	s_waitcnt lgkmcnt(0)
	v_mfma_f32_32x32x16_bf16 v[82:97], v[34:37], v[126:129], v[82:97]
	s_nop 8
	v_add_f32_e64 v50, v66, -v224
	v_add_f32_e64 v51, v67, -v224
	v_add_f32_e64 v52, v68, -v224
	v_add_f32_e64 v53, v69, -v224
	v_add_f32_e64 v54, v70, -v224
	v_add_f32_e64 v55, v71, -v224
	v_pk_add_f32 v[56:57], v[72:73], v[224:225] op_sel_hi:[1,0] neg_lo:[0,1] neg_hi:[0,1]
	v_pk_add_f32 v[58:59], v[74:75], v[224:225] op_sel_hi:[1,0] neg_lo:[0,1] neg_hi:[0,1]
	v_pk_add_f32 v[60:61], v[76:77], v[224:225] op_sel_hi:[1,0] neg_lo:[0,1] neg_hi:[0,1]
	v_pk_add_f32 v[62:63], v[78:79], v[224:225] op_sel_hi:[1,0] neg_lo:[0,1] neg_hi:[0,1]
	v_pk_add_f32 v[34:35], v[82:83], v[224:225] op_sel_hi:[1,0] neg_lo:[0,1] neg_hi:[0,1]
	v_pk_add_f32 v[36:37], v[84:85], v[224:225] op_sel_hi:[1,0] neg_lo:[0,1] neg_hi:[0,1]
	v_pk_add_f32 v[38:39], v[86:87], v[224:225] op_sel_hi:[1,0] neg_lo:[0,1] neg_hi:[0,1]
	v_pk_add_f32 v[40:41], v[88:89], v[224:225] op_sel_hi:[1,0] neg_lo:[0,1] neg_hi:[0,1]
	v_pk_add_f32 v[42:43], v[90:91], v[224:225] op_sel_hi:[1,0] neg_lo:[0,1] neg_hi:[0,1]
	v_pk_add_f32 v[44:45], v[92:93], v[224:225] op_sel_hi:[1,0] neg_lo:[0,1] neg_hi:[0,1]
	v_pk_add_f32 v[46:47], v[94:95], v[224:225] op_sel_hi:[1,0] neg_lo:[0,1] neg_hi:[0,1]
	v_pk_add_f32 v[64:65], v[80:81], v[224:225] op_sel_hi:[1,0] neg_lo:[0,1] neg_hi:[0,1]
	v_pk_add_f32 v[48:49], v[96:97], v[224:225] op_sel_hi:[1,0] neg_lo:[0,1] neg_hi:[0,1]
	v_lshl_add_u64 v[66:67], v[222:223], 0, s[38:39]
	s_mov_b32 m0, s71
	s_nop 0
	global_load_lds_dwordx4 v[66:67], off
	v_max_f32_e32 v66, v50, v51
	v_max3_f32 v67, v52, v53, v35
	v_max3_f32 v66, v66, v34, v36
	v_max3_f32 v66, v66, v37, v54
	v_max3_f32 v67, v67, v56, v57
	v_max3_f32 v66, v66, v55, v38
	v_max3_f32 v67, v67, v40, v41
	v_max3_f32 v66, v66, v39, v58
	v_max3_f32 v67, v67, v60, v61
	v_max3_f32 v66, v66, v59, v42
	v_max3_f32 v67, v67, v44, v45
	v_max3_f32 v66, v66, v43, v62
	v_max3_f32 v67, v67, v64, v65
	v_max3_f32 v66, v66, v63, v46
	v_max3_f32 v67, v67, v48, v49
	v_max3_f32 v66, v66, v47, v67
	v_mov_b32_e32 v67, v66
	s_nop 1
	v_permlane32_swap_b32_e32 v66, v67
	v_max_f32_e32 v66, v66, v67
	v_cmp_lt_f32_e32 vcc, s27, v66
	s_cmp_lg_u64 vcc, 0
	s_cselect_b64 s[4:5], -1, 0
	s_cbranch_vccnz .LBB0_590

.LBB0_543:
	ds_read_b64_tr_b16 v[166:167], v228 offset:61440
	ds_read_b64_tr_b16 v[168:169], v228 offset:61952
	v_add_f32_e32 v70, v50, v51
	v_add_f32_e32 v70, v52, v70
	v_add_f32_e32 v70, v53, v70
	v_add_f32_e32 v70, v54, v70
	v_add_f32_e32 v86, v55, v70
	s_waitcnt lgkmcnt(9)
	v_mfma_f32_32x32x16_bf16 v[66:81], v[66:69], v[110:113], 0
	v_cvt_pk_bf16_f32 v134, v50, v51
	v_cvt_pk_bf16_f32 v135, v52, v53
	ds_read_b64_tr_b16 v[158:159], v229 offset:28672
	ds_read_b64_tr_b16 v[160:161], v229 offset:29184
	v_add_f32_e32 v50, v56, v86
	v_add_f32_e32 v50, v57, v50
	v_add_f32_e32 v50, v58, v50
	v_add_f32_e32 v50, v59, v50
	v_cvt_pk_bf16_f32 v136, v54, v55
	v_cvt_pk_bf16_f32 v137, v56, v57
	s_waitcnt lgkmcnt(10)
	v_mfma_f32_32x32x16_bf16 v[82:97], v[82:85], v[110:113], 0
	ds_read_b64_tr_b16 v[146:147], v228 offset:62464
	ds_read_b64_tr_b16 v[148:149], v228 offset:62976
	s_waitcnt lgkmcnt(11)
	v_mfma_f32_32x32x16_bf16 v[66:81], v[186:189], v[106:109], v[66:81]
	v_add_f32_e32 v50, v60, v50
	v_add_f32_e32 v50, v61, v50
	v_add_f32_e32 v50, v62, v50
	v_add_f32_e32 v50, v63, v50
	v_cvt_pk_bf16_f32 v130, v58, v59
	v_cvt_pk_bf16_f32 v131, v60, v61
	ds_read_b64_tr_b16 v[150:151], v229 offset:29696
	ds_read_b64_tr_b16 v[152:153], v229 offset:30208
	v_add_f32_e32 v50, v64, v50
	v_add_f32_e32 v50, v65, v50
	v_add_f32_e32 v50, v34, v50
	v_add_f32_e32 v50, v35, v50
	v_cvt_pk_bf16_f32 v132, v62, v63
	v_cvt_pk_bf16_f32 v133, v64, v65
	s_waitcnt lgkmcnt(12)
	v_mfma_f32_32x32x16_bf16 v[82:97], v[182:185], v[106:109], v[82:97]
	ds_read_b64_tr_b16 v[162:163], v228 offset:63488
	ds_read_b64_tr_b16 v[164:165], v228 offset:64000
	s_waitcnt lgkmcnt(13)
	v_mfma_f32_32x32x16_bf16 v[66:81], v[178:181], v[102:105], v[66:81]
	v_add_f32_e32 v50, v36, v50
	v_add_f32_e32 v50, v37, v50
	v_add_f32_e32 v50, v38, v50
	v_add_f32_e32 v50, v39, v50
	v_cvt_pk_bf16_f32 v122, v34, v35
	v_cvt_pk_bf16_f32 v123, v36, v37
	ds_read_b64_tr_b16 v[138:139], v229 offset:30720
	ds_read_b64_tr_b16 v[140:141], v229 offset:31232
	v_add_f32_e32 v34, v40, v50
	v_add_f32_e32 v34, v41, v34
	v_add_f32_e32 v34, v42, v34
	v_add_f32_e32 v34, v43, v34
	v_cvt_pk_bf16_f32 v124, v38, v39
	v_cvt_pk_bf16_f32 v125, v40, v41
	s_waitcnt lgkmcnt(14)
	v_mfma_f32_32x32x16_bf16 v[82:97], v[154:157], v[102:105], v[82:97]
	ds_read_b64_tr_b16 v[142:143], v228 offset:64512
	ds_read_b64_tr_b16 v[144:145], v228 offset:65024
	s_waitcnt lgkmcnt(14)
	v_mfma_f32_32x32x16_bf16 v[66:81], v[174:177], v[98:101], v[66:81]
	v_add_f32_e32 v34, v44, v34
	v_add_f32_e32 v34, v45, v34
	v_add_f32_e32 v34, v46, v34
	v_add_f32_e32 v34, v47, v34
	v_cvt_pk_bf16_f32 v118, v42, v43
	v_cvt_pk_bf16_f32 v119, v44, v45
	ds_read_b64_tr_b16 v[154:155], v229 offset:31744
	ds_read_b64_tr_b16 v[156:157], v229 offset:32256
	v_add_f32_e32 v34, v48, v34
	v_add_f32_e32 v34, v49, v34
	v_mfma_f32_32x32x16_bf16 v[82:97], v[170:173], v[98:101], v[82:97]
	v_add_f32_e32 v170, 0, v34
	v_cvt_pk_bf16_f32 v120, v46, v47
	v_cvt_pk_bf16_f32 v121, v48, v49
	ds_read_b128 v[34:37], v207 offset:8192
	v_add_f32_e32 v178, v219, v170
	s_waitcnt lgkmcnt(0)
	v_mfma_f32_32x32x16_bf16 v[66:81], v[34:37], v[114:117], v[66:81]
	ds_read_b128 v[34:37], v207 offset:8704
	s_waitcnt lgkmcnt(0)
	v_mfma_f32_32x32x16_bf16 v[82:97], v[34:37], v[114:117], v[82:97]
	ds_read_b128 v[34:37], v207 offset:10240
	s_waitcnt lgkmcnt(0)
	v_mfma_f32_32x32x16_bf16 v[66:81], v[34:37], v[126:129], v[66:81]
	ds_read_b128 v[34:37], v207 offset:10752
	s_waitcnt lgkmcnt(0)
	v_mfma_f32_32x32x16_bf16 v[82:97], v[34:37], v[126:129], v[82:97]
	s_nop 8
	v_add_f32_e64 v50, v66, -v224
	v_add_f32_e64 v51, v67, -v224
	v_add_f32_e64 v52, v68, -v224
	v_add_f32_e64 v53, v69, -v224
	v_add_f32_e64 v54, v70, -v224
	v_add_f32_e64 v55, v71, -v224
	v_pk_add_f32 v[56:57], v[72:73], v[224:225] op_sel_hi:[1,0] neg_lo:[0,1] neg_hi:[0,1]
	v_pk_add_f32 v[58:59], v[74:75], v[224:225] op_sel_hi:[1,0] neg_lo:[0,1] neg_hi:[0,1]
	v_pk_add_f32 v[60:61], v[76:77], v[224:225] op_sel_hi:[1,0] neg_lo:[0,1] neg_hi:[0,1]
	v_pk_add_f32 v[62:63], v[78:79], v[224:225] op_sel_hi:[1,0] neg_lo:[0,1] neg_hi:[0,1]
	v_pk_add_f32 v[34:35], v[82:83], v[224:225] op_sel_hi:[1,0] neg_lo:[0,1] neg_hi:[0,1]
	v_pk_add_f32 v[36:37], v[84:85], v[224:225] op_sel_hi:[1,0] neg_lo:[0,1] neg_hi:[0,1]
	v_pk_add_f32 v[38:39], v[86:87], v[224:225] op_sel_hi:[1,0] neg_lo:[0,1] neg_hi:[0,1]
	v_pk_add_f32 v[40:41], v[88:89], v[224:225] op_sel_hi:[1,0] neg_lo:[0,1] neg_hi:[0,1]
	v_pk_add_f32 v[42:43], v[90:91], v[224:225] op_sel_hi:[1,0] neg_lo:[0,1] neg_hi:[0,1]
	v_pk_add_f32 v[44:45], v[92:93], v[224:225] op_sel_hi:[1,0] neg_lo:[0,1] neg_hi:[0,1]
	v_pk_add_f32 v[46:47], v[94:95], v[224:225] op_sel_hi:[1,0] neg_lo:[0,1] neg_hi:[0,1]
	v_pk_add_f32 v[64:65], v[80:81], v[224:225] op_sel_hi:[1,0] neg_lo:[0,1] neg_hi:[0,1]
	v_pk_add_f32 v[48:49], v[96:97], v[224:225] op_sel_hi:[1,0] neg_lo:[0,1] neg_hi:[0,1]
	v_lshl_add_u64 v[66:67], v[222:223], 0, s[40:41]
	s_mov_b32 m0, s36
	s_nop 0
	global_load_lds_dwordx4 v[66:67], off
	v_max_f32_e32 v66, v50, v51
	v_max3_f32 v67, v52, v53, v35
	v_max3_f32 v66, v66, v34, v36
	v_max3_f32 v66, v66, v37, v54
	v_max3_f32 v67, v67, v56, v57
	v_max3_f32 v66, v66, v55, v38
	v_max3_f32 v67, v67, v40, v41
	v_max3_f32 v66, v66, v39, v58
	v_max3_f32 v67, v67, v60, v61
	v_max3_f32 v66, v66, v59, v42
	v_max3_f32 v67, v67, v44, v45
	v_max3_f32 v66, v66, v43, v62
	v_max3_f32 v67, v67, v64, v65
	v_max3_f32 v66, v66, v63, v46
	v_max3_f32 v67, v67, v48, v49
	v_max3_f32 v66, v66, v47, v67
	v_mov_b32_e32 v67, v66
	s_nop 1
	v_permlane32_swap_b32_e32 v66, v67
	v_max_f32_e32 v66, v66, v67
	v_cmp_lt_f32_e32 vcc, s27, v66
	s_cmp_lg_u64 vcc, 0
	s_cselect_b64 s[4:5], -1, 0
	s_cbranch_vccnz .LBB0_593

.LBB0_552:
	s_lshl_b32 s7, s75, 21
	s_and_b32 s34, s77, 0x80
	s_lshl_b32 s36, s74, 6
	s_lshl_b32 s4, s79, 10
	s_add_u32 s4, s29, s4
	s_addc_u32 s5, s31, 0
	s_lshl_b32 s6, s74, 7
	s_add_u32 s6, s4, s6
	s_addc_u32 s37, s5, 0
	s_lshl_b32 s18, s83, 8
	s_add_u32 s4, s33, s18
	s_addc_u32 s5, s3, 0
	s_lshl_b32 s19, s81, 5
	s_and_b32 s19, s19, 0x80
	s_add_u32 s4, s4, s19
	s_addc_u32 s5, s5, 0
	v_readlane_b32 s30, v254, 34
	s_add_u32 s18, s30, s18
	v_readlane_b32 s30, v254, 35
	s_addc_u32 s30, s30, 0
	s_add_u32 s18, s18, s19
	v_readfirstlane_b32 s35, v192
	s_addc_u32 s19, s30, 0
	s_lshr_b32 s30, s35, 6
	s_lshl_b32 s72, s30, 5
	s_lshl_b64 s[38:39], s[72:73], 10
	s_add_u32 s42, s6, s38
	v_mov_b32_e32 v219, v1
	s_addc_u32 s43, s37, s39
	v_lshl_add_u64 v[2:3], s[4:5], 0, v[218:219]
	s_lshl_b32 s4, s30, 4
	s_mov_b32 s5, s73
	v_and_or_b32 v0, s4, 48, v193
	v_lshl_add_u64 v[224:225], v[2:3], 0, s[4:5]
	v_lshlrev_b32_e32 v0, 8, v0
	s_lshr_b32 s5, s35, 2
	s_and_b32 s39, s35, 0x3fffffc0
	v_lshl_add_u64 v[2:3], s[18:19], 0, v[0:1]
	s_and_b32 s18, s5, 0x3fffffc0
	s_lshl_b32 s38, s30, 10
	s_cmp_lg_u32 0, -1
	s_mov_b32 s19, s73
	s_cselect_b32 s5, 0, 0
	v_lshl_add_u64 v[2:3], v[2:3], 0, s[18:19]
	v_mov_b32_e32 v221, v1
	s_add_i32 s40, s38, s5
	s_mov_b32 m0, s40
	s_nop 0
	global_load_lds_dwordx4 v[224:225], off
	v_lshl_add_u64 v[222:223], v[2:3], 0, v[220:221]
	s_add_i32 s37, s40, 0x6000
	s_mov_b32 m0, s37
	s_nop 0
	global_load_lds_dwordx4 v[222:223], off
	v_lshl_add_u64 v[2:3], v[224:225], 0, s[94:95]
	s_add_i32 s5, s40, 0x2000
	s_mov_b32 m0, s5
	s_nop 0
	global_load_lds_dwordx4 v[2:3], off
	global_load_dwordx4 v[158:161], v241, s[42:43]
	global_load_dwordx4 v[150:153], v241, s[42:43] offset:32
	global_load_dwordx4 v[142:145], v241, s[42:43] offset:64
	global_load_dwordx4 v[134:137], v241, s[42:43] offset:96
	v_mov_b32_e32 v2, v1
	v_mov_b32_e32 v3, v1
	v_mov_b32_e32 v4, v1
	v_mov_b32_e32 v5, v1
	v_mov_b32_e32 v6, v1
	v_mov_b32_e32 v7, v1
	v_mov_b32_e32 v8, v1
	v_mov_b32_e32 v9, v1
	v_mov_b32_e32 v10, v1
	v_mov_b32_e32 v11, v1
	v_mov_b32_e32 v12, v1
	v_mov_b32_e32 v13, v1
	v_mov_b32_e32 v14, v1
	v_mov_b32_e32 v15, v1
	v_mov_b32_e32 v0, v1
	v_mov_b64_e32 v[16:17], v[14:15]
	v_mov_b64_e32 v[14:15], v[12:13]
	v_mov_b64_e32 v[12:13], v[10:11]
	v_mov_b64_e32 v[10:11], v[8:9]
	v_mov_b64_e32 v[8:9], v[6:7]
	v_mov_b64_e32 v[6:7], v[4:5]
	v_mov_b64_e32 v[4:5], v[2:3]
	v_mov_b64_e32 v[2:3], v[0:1]
	v_lshl_add_u64 v[18:19], v[224:225], 0, s[14:15]
	s_add_i32 s5, s40, 0x4000
	s_mov_b32 m0, s5
	s_nop 0
	global_load_lds_dwordx4 v[18:19], off
	s_waitcnt vmcnt(3) lgkmcnt(0)
	s_barrier
	ds_read_b128 v[34:37], v207
	ds_read_b128 v[38:41], v207 offset:512
	s_lshl_b32 s19, s39, 2
	s_add_i32 s39, s19, 0
	s_or_b32 s7, s7, s34
	s_mov_b32 s41, -1
	s_mov_b32 s5, 0
	s_movk_i32 s6, 0x2000
	s_movk_i32 s42, 0x4000
	v_lshl_add_u32 v217, v191, 2, s39
	s_waitcnt vmcnt(3) lgkmcnt(1)
	v_mfma_f32_32x32x16_bf16 v[18:33], v[34:37], v[158:161], v[2:17]
	s_waitcnt lgkmcnt(0)
	v_mfma_f32_32x32x16_bf16 v[2:17], v[38:41], v[158:161], v[2:17]
	ds_read_b128 v[34:37], v207 offset:2048
	ds_read_b128 v[38:41], v207 offset:2560
	s_waitcnt vmcnt(2) lgkmcnt(1)
	v_mfma_f32_32x32x16_bf16 v[18:33], v[34:37], v[150:153], v[18:33]
	s_waitcnt lgkmcnt(0)
	v_mfma_f32_32x32x16_bf16 v[2:17], v[38:41], v[150:153], v[2:17]
	ds_read_b128 v[34:37], v207 offset:4096
	ds_read_b128 v[38:41], v207 offset:4608
	s_waitcnt vmcnt(1) lgkmcnt(1)
	v_mfma_f32_32x32x16_bf16 v[18:33], v[34:37], v[142:145], v[18:33]
	s_waitcnt lgkmcnt(0)
	v_mfma_f32_32x32x16_bf16 v[2:17], v[38:41], v[142:145], v[2:17]
	ds_read_b128 v[34:37], v207 offset:6144
	ds_read_b128 v[38:41], v207 offset:6656
	s_waitcnt vmcnt(0) lgkmcnt(1)
	v_mfma_f32_32x32x16_bf16 v[18:33], v[34:37], v[134:137], v[18:33]
	s_waitcnt lgkmcnt(0)
	v_mfma_f32_32x32x16_bf16 v[2:17], v[38:41], v[134:137], v[2:17]
	s_nop 15
	s_nop 7
	s_nop 0
	v_max3_f32 v0, v18, v19, v2
	v_max3_f32 v34, v20, v21, v3
	s_nop 0
	v_max3_f32 v0, v0, v4, v5
	v_max3_f32 v34, v34, v24, v25
	s_nop 0
	v_max3_f32 v0, v0, v22, v23
	v_max3_f32 v34, v34, v8, v9
	s_nop 0
	v_max3_f32 v0, v0, v6, v7
	v_max3_f32 v34, v34, v28, v29
	s_nop 0
	v_max3_f32 v0, v0, v26, v27
	v_max3_f32 v34, v34, v12, v13
	s_nop 0
	v_max3_f32 v0, v0, v10, v11
	v_max3_f32 v34, v34, v32, v33
	s_nop 0
	v_max3_f32 v0, v0, v30, v31
	v_max3_f32 v34, v34, v16, v17
	s_nop 0
	v_max3_f32 v0, v0, v14, v15
	s_nop 0
	v_max_f32_e32 v0, v0, v34
	s_nop 0
	v_mov_b32_e32 v34, v0
	s_nop 1
	v_permlane32_swap_b32_e32 v0, v34
	v_max_f32_e32 v0, v0, v34
	s_nop 0
	v_add_f32_e32 v219, v1, v0
	v_sub_f32_e32 v2, v2, v0
	v_sub_f32_e32 v3, v3, v0
	v_sub_f32_e32 v18, v18, v0
	v_sub_f32_e32 v19, v19, v0
	v_sub_f32_e32 v20, v20, v0
	s_nop 0
	v_xor_b32_e32 v34, 0x80000000, v219
	v_mov_b32_e32 v35, v34
	v_mov_b32_e32 v36, v34
	v_mov_b32_e32 v37, v34
	v_mov_b32_e32 v38, v34
	v_mov_b32_e32 v39, v34
	v_mov_b32_e32 v40, v34
	v_mov_b32_e32 v41, v34
	v_mov_b32_e32 v42, v34
	v_mov_b32_e32 v43, v34
	v_mov_b32_e32 v44, v34
	v_mov_b32_e32 v45, v34
	v_mov_b32_e32 v46, v34
	v_mov_b32_e32 v47, v34
	v_mov_b32_e32 v48, v34
	v_mov_b32_e32 v49, v34
	s_waitcnt vmcnt(0) lgkmcnt(0)
	s_barrier
	v_exp_f32_e32 v50, v2
	v_exp_f32_e32 v51, v3
	v_lshl_add_u64 v[2:3], v[224:225], 0, s[62:63]
	s_mov_b32 m0, s40
	s_nop 0
	global_load_lds_dwordx4 v[2:3], off
	v_lshl_add_u64 v[2:3], v[222:223], 0, s[94:95]
	s_add_i32 s19, s40, 0x8000
	s_mov_b32 m0, s19
	s_nop 0
	global_load_lds_dwordx4 v[2:3], off
	ds_read_b128 v[82:85], v207 offset:8192
	ds_read_b128 v[166:169], v207 offset:8704
	ds_read_b128 v[170:173], v207 offset:10240
	ds_read_b128 v[162:165], v207 offset:10752
	ds_read_b128 v[126:129], v207 offset:12288
	ds_read_b128 v[122:125], v207 offset:12800
	ds_read_b128 v[118:121], v207 offset:14336
	ds_read_b128 v[114:117], v207 offset:14848
	s_add_u32 s44, s7, s4
	s_addc_u32 s45, 0, 0
	s_add_u32 s18, s7, s18
	s_addc_u32 s19, 0, 0
	s_lshl_b32 s4, s35, 6
	v_sub_f32_e32 v4, v4, v0
	v_sub_f32_e32 v21, v21, v0
	v_sub_f32_e32 v5, v5, v0
	v_sub_f32_e32 v22, v22, v0
	v_sub_f32_e32 v6, v6, v0
	v_sub_f32_e32 v23, v23, v0
	v_sub_f32_e32 v7, v7, v0
	v_sub_f32_e32 v24, v24, v0
	v_sub_f32_e32 v8, v8, v0
	v_sub_f32_e32 v25, v25, v0
	v_sub_f32_e32 v9, v9, v0
	v_sub_f32_e32 v26, v26, v0
	v_sub_f32_e32 v10, v10, v0
	v_sub_f32_e32 v27, v27, v0
	v_sub_f32_e32 v11, v11, v0
	v_sub_f32_e32 v28, v28, v0
	v_sub_f32_e32 v12, v12, v0
	v_sub_f32_e32 v29, v29, v0
	v_sub_f32_e32 v13, v13, v0
	v_sub_f32_e32 v30, v30, v0
	v_sub_f32_e32 v14, v14, v0
	v_sub_f32_e32 v31, v31, v0
	v_sub_f32_e32 v15, v15, v0
	v_sub_f32_e32 v32, v32, v0
	v_sub_f32_e32 v16, v16, v0
	v_sub_f32_e32 v33, v33, v0
	v_sub_f32_e32 v0, v17, v0
	v_exp_f32_e32 v66, v18
	v_exp_f32_e32 v67, v19
	v_exp_f32_e32 v68, v20
	v_exp_f32_e32 v69, v21
	v_exp_f32_e32 v70, v22
	v_exp_f32_e32 v71, v23
	v_exp_f32_e32 v72, v24
	v_exp_f32_e32 v73, v25
	v_exp_f32_e32 v74, v26
	v_exp_f32_e32 v75, v27
	v_exp_f32_e32 v76, v28
	v_exp_f32_e32 v77, v29
	v_exp_f32_e32 v78, v30
	v_exp_f32_e32 v79, v31
	v_exp_f32_e32 v80, v32
	v_exp_f32_e32 v81, v33
	v_exp_f32_e32 v52, v4
	v_exp_f32_e32 v53, v5
	v_exp_f32_e32 v54, v6
	v_exp_f32_e32 v55, v7
	v_exp_f32_e32 v56, v8
	v_exp_f32_e32 v57, v9
	v_exp_f32_e32 v58, v10
	v_exp_f32_e32 v59, v11
	v_exp_f32_e32 v60, v12
	v_exp_f32_e32 v61, v13
	v_exp_f32_e32 v62, v14
	v_exp_f32_e32 v63, v15
	v_exp_f32_e32 v64, v16
	v_exp_f32_e32 v65, v0
	s_and_b32 s4, s4, 0x3000
	s_waitcnt vmcnt(2) lgkmcnt(0)
	s_barrier
	v_lshl_or_b32 v0, v238, 1, s4
	v_lshl_add_u64 v[2:3], s[18:19], 0, v[0:1]
	v_mov_b32_e32 v0, 0
	v_lshl_add_u64 v[182:183], v[212:213], 0, s[44:45]
	v_lshl_add_u64 v[184:185], v[214:215], 0, v[2:3]
	v_mov_b32_e32 v2, 0
	v_mov_b32_e32 v3, v0
	v_mov_b32_e32 v4, v0
	v_mov_b32_e32 v5, v0
	v_mov_b32_e32 v6, v0
	v_mov_b32_e32 v7, v0
	v_mov_b32_e32 v8, v0
	v_mov_b32_e32 v9, v0
	v_mov_b32_e32 v10, v0
	v_mov_b32_e32 v11, v0
	v_mov_b32_e32 v12, v0
	v_mov_b32_e32 v13, v0
	v_mov_b32_e32 v14, v0
	v_mov_b32_e32 v15, v0
	v_mov_b32_e32 v16, v0
	v_mov_b32_e32 v17, v0
	v_mov_b32_e32 v18, 0
	v_mov_b32_e32 v19, v0
	v_mov_b32_e32 v20, v0
	v_mov_b32_e32 v21, v0
	v_mov_b32_e32 v22, v0
	v_mov_b32_e32 v23, v0
	v_mov_b32_e32 v24, v0
	v_mov_b32_e32 v25, v0
	v_mov_b32_e32 v26, v0
	v_mov_b32_e32 v27, v0
	v_mov_b32_e32 v28, v0
	v_mov_b32_e32 v29, v0
	v_mov_b32_e32 v30, v0
	v_mov_b32_e32 v31, v0
	v_mov_b32_e32 v32, v0
	v_mov_b32_e32 v33, v0
.LBB0_553:
	v_add_u32_e32 v186, s5, v228
	ds_read_b64_tr_b16 v[178:179], v186 offset:24576
	ds_read_b64_tr_b16 v[180:181], v186 offset:25088
	s_waitcnt lgkmcnt(9)
	v_mfma_f32_32x32x16_bf16 v[98:113], v[82:85], v[158:161], v[34:49]
	v_add_f32_e32 v86, v66, v67
	v_add_f32_e32 v86, v68, v86
	v_add_f32_e32 v86, v69, v86
	v_add_f32_e32 v86, v70, v86
	v_add_f32_e32 v86, v71, v86
	v_cvt_pk_bf16_f32 v154, v66, v67
	v_cvt_pk_bf16_f32 v155, v68, v69
	ds_read_b64_tr_b16 v[174:175], v186 offset:28672
	ds_read_b64_tr_b16 v[176:177], v186 offset:29184
	v_add_f32_e32 v66, v72, v86
	s_waitcnt lgkmcnt(10)
	v_mfma_f32_32x32x16_bf16 v[82:97], v[166:169], v[158:161], v[34:49]
	v_add_f32_e32 v66, v73, v66
	v_add_f32_e32 v66, v74, v66
	v_add_f32_e32 v130, v75, v66
	v_cvt_pk_bf16_f32 v156, v70, v71
	v_cvt_pk_bf16_f32 v157, v72, v73
	ds_read_b64_tr_b16 v[66:67], v186 offset:25600
	ds_read_b64_tr_b16 v[68:69], v186 offset:26112
	s_waitcnt lgkmcnt(11)
	v_mfma_f32_32x32x16_bf16 v[98:113], v[170:173], v[150:153], v[98:113]
	v_add_f32_e32 v70, v76, v130
	v_add_f32_e32 v70, v77, v70
	v_add_f32_e32 v70, v78, v70
	v_add_f32_e32 v130, v79, v70
	v_cvt_pk_bf16_f32 v146, v74, v75
	v_cvt_pk_bf16_f32 v147, v76, v77
	ds_read_b64_tr_b16 v[70:71], v186 offset:29696
	ds_read_b64_tr_b16 v[72:73], v186 offset:30208
	s_waitcnt lgkmcnt(12)
	v_mfma_f32_32x32x16_bf16 v[82:97], v[162:165], v[150:153], v[82:97]
	v_add_f32_e32 v74, v80, v130
	v_add_f32_e32 v74, v81, v74
	v_add_f32_e32 v74, v50, v74
	v_add_f32_e32 v130, v51, v74
	v_cvt_pk_bf16_f32 v148, v78, v79
	v_cvt_pk_bf16_f32 v149, v80, v81
	ds_read_b64_tr_b16 v[74:75], v186 offset:26624
	ds_read_b64_tr_b16 v[76:77], v186 offset:27136
	s_waitcnt lgkmcnt(13)
	v_mfma_f32_32x32x16_bf16 v[98:113], v[126:129], v[142:145], v[98:113]
	v_add_f32_e32 v78, v52, v130
	v_add_f32_e32 v78, v53, v78
	v_add_f32_e32 v78, v54, v78
	v_add_f32_e32 v78, v55, v78
	v_cvt_pk_bf16_f32 v138, v50, v51
	v_cvt_pk_bf16_f32 v139, v52, v53
	ds_read_b64_tr_b16 v[50:51], v186 offset:30720
	ds_read_b64_tr_b16 v[52:53], v186 offset:31232
	s_waitcnt lgkmcnt(14)
	v_mfma_f32_32x32x16_bf16 v[82:97], v[122:125], v[142:145], v[82:97]
	v_add_f32_e32 v78, v56, v78
	v_add_f32_e32 v78, v57, v78
	v_add_f32_e32 v78, v58, v78
	v_add_f32_e32 v78, v59, v78
	v_cvt_pk_bf16_f32 v140, v54, v55
	v_cvt_pk_bf16_f32 v141, v56, v57
	ds_read_b64_tr_b16 v[54:55], v186 offset:27648
	ds_read_b64_tr_b16 v[56:57], v186 offset:28160
	s_waitcnt lgkmcnt(14)
	v_mfma_f32_32x32x16_bf16 v[98:113], v[118:121], v[134:137], v[98:113]
	v_add_f32_e32 v78, v60, v78
	v_add_f32_e32 v78, v61, v78
	v_add_f32_e32 v78, v62, v78
	v_add_f32_e32 v78, v63, v78
	v_cvt_pk_bf16_f32 v130, v58, v59
	v_cvt_pk_bf16_f32 v131, v60, v61
	ds_read_b64_tr_b16 v[58:59], v186 offset:31744
	ds_read_b64_tr_b16 v[60:61], v186 offset:32256
	v_mfma_f32_32x32x16_bf16 v[82:97], v[114:117], v[134:137], v[82:97]
	v_add_f32_e32 v78, v64, v78
	v_add_f32_e32 v78, v65, v78
	v_cvt_pk_bf16_f32 v132, v62, v63
	v_cvt_pk_bf16_f32 v133, v64, v65
	v_lshl_add_u64 v[62:63], v[182:183], 0, s[62:63]
	s_add_i32 s4, s6, s40
	s_mov_b32 m0, s4
	s_nop 0
	global_load_lds_dwordx4 v[62:63], off
	v_lshl_add_u64 v[62:63], v[184:185], 0, s[94:95]
	s_add_i32 s4, s42, s37
	s_mov_b32 m0, s4
	s_nop 0
	global_load_lds_dwordx4 v[62:63], off
	v_max_f32_e32 v62, v99, v99
	v_max_f32_e32 v63, v98, v98
	v_max_f32_e32 v62, v63, v62
	v_max3_f32 v63, v100, v101, v83
	v_max3_f32 v62, v62, v82, v84
	v_max3_f32 v62, v62, v85, v102
	v_max3_f32 v63, v63, v104, v105
	v_max3_f32 v62, v62, v103, v86
	v_max3_f32 v63, v63, v88, v89
	v_max3_f32 v62, v62, v87, v106
	v_max3_f32 v63, v63, v108, v109
	v_max3_f32 v62, v62, v107, v90
	v_max3_f32 v63, v63, v92, v93
	v_max3_f32 v62, v62, v91, v110
	v_max3_f32 v63, v63, v112, v113
	v_max3_f32 v62, v62, v111, v94
	v_max3_f32 v63, v63, v96, v97
	v_max3_f32 v62, v62, v95, v63
	v_mov_b32_e32 v63, v62
	s_nop 1
	v_permlane32_swap_b32_e32 v62, v63
	v_max_f32_e32 v62, v62, v63
	v_cmp_lt_f32_e32 vcc, s27, v62
	s_cmp_lg_u64 vcc, 0
	v_add_f32_e32 v0, v0, v78
	s_cselect_b64 s[4:5], -1, 0
	s_cbranch_vccnz .LBB0_561

.LBB0_556:
	s_add_i32 s4, s42, 0x2000
	s_cmpk_lg_i32 s42, 0x4000
	s_cselect_b32 s7, s4, 0
	v_add_u32_e32 v186, s6, v228
	ds_read_b64_tr_b16 v[118:119], v186 offset:24576
	ds_read_b64_tr_b16 v[120:121], v186 offset:25088
	s_waitcnt lgkmcnt(9)
	v_mfma_f32_32x32x16_bf16 v[66:81], v[62:65], v[158:161], v[34:49]
	v_add_f32_e32 v50, v98, v99
	v_add_f32_e32 v50, v100, v50
	v_add_f32_e32 v50, v101, v50
	v_add_f32_e32 v50, v102, v50
	v_add_f32_e32 v50, v103, v50
	v_cvt_pk_bf16_f32 v154, v98, v99
	v_cvt_pk_bf16_f32 v155, v100, v101
	ds_read_b64_tr_b16 v[114:115], v186 offset:28672
	ds_read_b64_tr_b16 v[116:117], v186 offset:29184
	v_add_f32_e32 v50, v104, v50
	v_add_f32_e32 v50, v105, v50
	v_add_f32_e32 v50, v106, v50
	v_add_f32_e32 v130, v107, v50
	s_waitcnt lgkmcnt(10)
	v_mfma_f32_32x32x16_bf16 v[50:65], v[174:177], v[158:161], v[34:49]
	v_cvt_pk_bf16_f32 v156, v102, v103
	v_cvt_pk_bf16_f32 v157, v104, v105
	ds_read_b64_tr_b16 v[98:99], v186 offset:25600
	ds_read_b64_tr_b16 v[100:101], v186 offset:26112
	s_waitcnt lgkmcnt(11)
	v_mfma_f32_32x32x16_bf16 v[66:81], v[178:181], v[150:153], v[66:81]
	v_add_f32_e32 v102, v108, v130
	v_add_f32_e32 v102, v109, v102
	v_add_f32_e32 v102, v110, v102
	v_add_f32_e32 v130, v111, v102
	v_cvt_pk_bf16_f32 v146, v106, v107
	v_cvt_pk_bf16_f32 v147, v108, v109
	ds_read_b64_tr_b16 v[102:103], v186 offset:29696
	ds_read_b64_tr_b16 v[104:105], v186 offset:30208
	s_waitcnt lgkmcnt(12)
	v_mfma_f32_32x32x16_bf16 v[50:65], v[170:173], v[150:153], v[50:65]
	v_add_f32_e32 v106, v112, v130
	v_add_f32_e32 v106, v113, v106
	v_add_f32_e32 v106, v82, v106
	v_add_f32_e32 v130, v83, v106
	v_cvt_pk_bf16_f32 v148, v110, v111
	v_cvt_pk_bf16_f32 v149, v112, v113
	ds_read_b64_tr_b16 v[106:107], v186 offset:26624
	ds_read_b64_tr_b16 v[108:109], v186 offset:27136
	s_waitcnt lgkmcnt(13)
	v_mfma_f32_32x32x16_bf16 v[66:81], v[166:169], v[142:145], v[66:81]
	v_add_f32_e32 v110, v84, v130
	v_add_f32_e32 v110, v85, v110
	v_add_f32_e32 v110, v86, v110
	v_add_f32_e32 v130, v87, v110
	v_cvt_pk_bf16_f32 v138, v82, v83
	v_cvt_pk_bf16_f32 v139, v84, v85
	ds_read_b64_tr_b16 v[110:111], v186 offset:30720
	ds_read_b64_tr_b16 v[112:113], v186 offset:31232
	s_waitcnt lgkmcnt(14)
	v_mfma_f32_32x32x16_bf16 v[50:65], v[162:165], v[142:145], v[50:65]
	v_add_f32_e32 v82, v88, v130
	v_add_f32_e32 v82, v89, v82
	v_add_f32_e32 v82, v90, v82
	v_add_f32_e32 v82, v91, v82
	v_cvt_pk_bf16_f32 v140, v86, v87
	v_cvt_pk_bf16_f32 v141, v88, v89
	ds_read_b64_tr_b16 v[86:87], v186 offset:27648
	ds_read_b64_tr_b16 v[88:89], v186 offset:28160
	s_waitcnt lgkmcnt(14)
	v_mfma_f32_32x32x16_bf16 v[66:81], v[126:129], v[134:137], v[66:81]
	v_add_f32_e32 v82, v92, v82
	v_add_f32_e32 v82, v93, v82
	v_add_f32_e32 v82, v94, v82
	v_add_f32_e32 v82, v95, v82
	v_cvt_pk_bf16_f32 v130, v90, v91
	v_cvt_pk_bf16_f32 v131, v92, v93
	ds_read_b64_tr_b16 v[90:91], v186 offset:31744
	ds_read_b64_tr_b16 v[92:93], v186 offset:32256
	v_mfma_f32_32x32x16_bf16 v[50:65], v[122:125], v[134:137], v[50:65]
	v_add_f32_e32 v82, v96, v82
	v_add_f32_e32 v82, v97, v82
	v_add_f32_e32 v84, 0, v82
	v_cvt_pk_bf16_f32 v132, v94, v95
	v_cvt_pk_bf16_f32 v133, v96, v97
	v_lshl_add_u64 v[82:83], v[182:183], 0, s[64:65]
	s_add_i32 s4, s42, s40
	s_mov_b32 m0, s4
	s_nop 0
	global_load_lds_dwordx4 v[82:83], off
	v_max_f32_e32 v82, v67, v67
	v_max_f32_e32 v83, v66, v66
	v_max_f32_e32 v82, v83, v82
	s_nop 1
	v_max3_f32 v83, v68, v69, v51
	v_max3_f32 v82, v82, v50, v52
	v_max3_f32 v82, v82, v53, v70
	v_max3_f32 v83, v83, v72, v73
	v_max3_f32 v82, v82, v71, v54
	v_max3_f32 v83, v83, v56, v57
	v_max3_f32 v82, v82, v55, v74
	v_max3_f32 v83, v83, v76, v77
	v_max3_f32 v82, v82, v75, v58
	v_max3_f32 v83, v83, v60, v61
	v_max3_f32 v82, v82, v59, v78
	v_max3_f32 v83, v83, v80, v81
	v_max3_f32 v82, v82, v79, v62
	v_max3_f32 v83, v83, v64, v65
	v_max3_f32 v82, v82, v63, v83
	v_mov_b32_e32 v83, v82
	s_nop 1
	v_permlane32_swap_b32_e32 v82, v83
	v_max_f32_e32 v82, v82, v83
	v_lshl_add_u64 v[184:185], v[184:185], 0, s[14:15]
	s_add_i32 s4, s7, s37
	s_mov_b32 m0, s4
	s_nop 0
	global_load_lds_dwordx4 v[184:185], off
	v_cmp_lt_f32_e32 vcc, s27, v82
	s_cmp_lg_u64 vcc, 0
	v_add_f32_e32 v0, v0, v84
	s_cselect_b64 s[4:5], -1, 0
	s_cbranch_vccnz .LBB0_564

.LBB0_567:
	ds_read_b64_tr_b16 v[178:179], v228 offset:40960
	ds_read_b64_tr_b16 v[180:181], v228 offset:41472
	s_waitcnt lgkmcnt(9)
	v_mfma_f32_32x32x16_bf16 v[98:113], v[82:85], v[158:161], v[34:49]
	v_add_f32_e32 v86, v66, v67
	v_add_f32_e32 v86, v68, v86
	v_add_f32_e32 v86, v69, v86
	v_add_f32_e32 v86, v70, v86
	v_add_f32_e32 v86, v71, v86
	v_cvt_pk_bf16_f32 v154, v66, v67
	v_cvt_pk_bf16_f32 v155, v68, v69
	ds_read_b64_tr_b16 v[174:175], v228 offset:45056
	ds_read_b64_tr_b16 v[176:177], v228 offset:45568
	v_add_f32_e32 v66, v72, v86
	s_waitcnt lgkmcnt(10)
	v_mfma_f32_32x32x16_bf16 v[82:97], v[166:169], v[158:161], v[34:49]
	v_add_f32_e32 v66, v73, v66
	v_add_f32_e32 v66, v74, v66
	v_add_f32_e32 v130, v75, v66
	v_cvt_pk_bf16_f32 v156, v70, v71
	v_cvt_pk_bf16_f32 v157, v72, v73
	ds_read_b64_tr_b16 v[66:67], v228 offset:41984
	ds_read_b64_tr_b16 v[68:69], v228 offset:42496
	s_waitcnt lgkmcnt(11)
	v_mfma_f32_32x32x16_bf16 v[98:113], v[170:173], v[150:153], v[98:113]
	v_add_f32_e32 v70, v76, v130
	v_add_f32_e32 v70, v77, v70
	v_add_f32_e32 v70, v78, v70
	v_add_f32_e32 v130, v79, v70
	v_cvt_pk_bf16_f32 v146, v74, v75
	v_cvt_pk_bf16_f32 v147, v76, v77
	ds_read_b64_tr_b16 v[70:71], v228 offset:46080
	ds_read_b64_tr_b16 v[72:73], v228 offset:46592
	s_waitcnt lgkmcnt(12)
	v_mfma_f32_32x32x16_bf16 v[82:97], v[162:165], v[150:153], v[82:97]
	v_add_f32_e32 v74, v80, v130
	v_add_f32_e32 v74, v81, v74
	v_add_f32_e32 v74, v50, v74
	v_add_f32_e32 v130, v51, v74
	v_cvt_pk_bf16_f32 v148, v78, v79
	v_cvt_pk_bf16_f32 v149, v80, v81
	ds_read_b64_tr_b16 v[74:75], v228 offset:43008
	ds_read_b64_tr_b16 v[76:77], v228 offset:43520
	s_waitcnt lgkmcnt(13)
	v_mfma_f32_32x32x16_bf16 v[98:113], v[126:129], v[142:145], v[98:113]
	v_add_f32_e32 v78, v52, v130
	v_add_f32_e32 v78, v53, v78
	v_add_f32_e32 v78, v54, v78
	v_add_f32_e32 v78, v55, v78
	v_cvt_pk_bf16_f32 v138, v50, v51
	v_cvt_pk_bf16_f32 v139, v52, v53
	ds_read_b64_tr_b16 v[50:51], v228 offset:47104
	ds_read_b64_tr_b16 v[52:53], v228 offset:47616
	s_waitcnt lgkmcnt(14)
	v_mfma_f32_32x32x16_bf16 v[82:97], v[122:125], v[142:145], v[82:97]
	v_add_f32_e32 v78, v56, v78
	v_add_f32_e32 v78, v57, v78
	v_add_f32_e32 v78, v58, v78
	v_add_f32_e32 v78, v59, v78
	v_cvt_pk_bf16_f32 v140, v54, v55
	v_cvt_pk_bf16_f32 v141, v56, v57
	ds_read_b64_tr_b16 v[54:55], v228 offset:44032
	ds_read_b64_tr_b16 v[56:57], v228 offset:44544
	s_waitcnt lgkmcnt(14)
	v_mfma_f32_32x32x16_bf16 v[98:113], v[118:121], v[134:137], v[98:113]
	v_add_f32_e32 v78, v60, v78
	v_add_f32_e32 v78, v61, v78
	v_add_f32_e32 v78, v62, v78
	v_add_f32_e32 v78, v63, v78
	v_cvt_pk_bf16_f32 v130, v58, v59
	v_cvt_pk_bf16_f32 v131, v60, v61
	ds_read_b64_tr_b16 v[58:59], v228 offset:48128
	ds_read_b64_tr_b16 v[60:61], v228 offset:48640
	v_mfma_f32_32x32x16_bf16 v[82:97], v[114:117], v[134:137], v[82:97]
	v_add_f32_e32 v78, v64, v78
	v_add_f32_e32 v78, v65, v78
	v_cvt_pk_bf16_f32 v132, v62, v63
	v_cvt_pk_bf16_f32 v133, v64, v65
	v_lshl_add_u64 v[62:63], v[224:225], 0, s[68:69]
	s_mov_b32 m0, s40
	s_nop 0
	global_load_lds_dwordx4 v[62:63], off
	s_mov_b64 s[4:5], 0x1f0000
	s_cmp_lg_u32 0, -1
	v_lshl_add_u64 v[62:63], v[222:223], 0, s[4:5]
	s_cselect_b32 s4, 0, 0
	s_add_i32 s4, s4, s38
	v_add_f32_e32 v221, v0, v78
	s_add_i32 s40, s4, 0x8000
	s_mov_b32 m0, s40
	s_nop 0
	global_load_lds_dwordx4 v[62:63], off
	v_max_f32_e32 v0, v99, v99
	v_max_f32_e32 v62, v98, v98
	v_max_f32_e32 v0, v62, v0
	v_max3_f32 v62, v100, v101, v83
	v_max3_f32 v0, v0, v82, v84
	v_max3_f32 v0, v0, v85, v102
	v_max3_f32 v62, v62, v104, v105
	v_max3_f32 v0, v0, v103, v86
	v_max3_f32 v62, v62, v88, v89
	v_max3_f32 v0, v0, v87, v106
	v_max3_f32 v62, v62, v108, v109
	v_max3_f32 v0, v0, v107, v90
	v_max3_f32 v62, v62, v92, v93
	v_max3_f32 v0, v0, v91, v110
	v_max3_f32 v62, v62, v112, v113
	v_max3_f32 v0, v0, v111, v94
	v_max3_f32 v62, v62, v96, v97
	v_max3_f32 v0, v0, v95, v62
	v_mov_b32_e32 v62, v0
	s_nop 1
	v_permlane32_swap_b32_e32 v0, v62
	v_max_f32_e32 v0, v0, v62
	v_cmp_lt_f32_e32 vcc, s27, v0
	s_cmp_lg_u64 vcc, 0
	s_cselect_b64 s[4:5], -1, 0
	s_cbranch_vccnz .LBB0_599

.LBB0_570:
	v_lshl_add_u64 v[224:225], v[224:225], 0, s[66:67]
	v_lshl_add_u64 v[226:227], v[222:223], 0, s[66:67]
	ds_read_b64_tr_b16 v[162:163], v228 offset:24576
	ds_read_b64_tr_b16 v[164:165], v228 offset:25088
	s_waitcnt lgkmcnt(9)
	v_mfma_f32_32x32x16_bf16 v[114:129], v[62:65], v[158:161], v[34:49]
	v_add_f32_e32 v50, v98, v99
	v_add_f32_e32 v50, v100, v50
	v_add_f32_e32 v50, v101, v50
	v_add_f32_e32 v50, v102, v50
	v_add_f32_e32 v50, v103, v50
	v_cvt_pk_bf16_f32 v154, v98, v99
	v_cvt_pk_bf16_f32 v155, v100, v101
	ds_read_b64_tr_b16 v[74:75], v228 offset:28672
	ds_read_b64_tr_b16 v[76:77], v228 offset:29184
	v_add_f32_e32 v50, v104, v50
	v_add_f32_e32 v50, v105, v50
	v_add_f32_e32 v50, v106, v50
	v_add_f32_e32 v70, v107, v50
	s_waitcnt lgkmcnt(10)
	v_mfma_f32_32x32x16_bf16 v[50:65], v[182:185], v[158:161], v[34:49]
	v_cvt_pk_bf16_f32 v156, v102, v103
	v_cvt_pk_bf16_f32 v157, v104, v105
	ds_read_b64_tr_b16 v[66:67], v228 offset:25600
	ds_read_b64_tr_b16 v[68:69], v228 offset:26112
	s_waitcnt lgkmcnt(11)
	v_mfma_f32_32x32x16_bf16 v[114:129], v[186:189], v[150:153], v[114:129]
	v_add_f32_e32 v70, v108, v70
	v_add_f32_e32 v70, v109, v70
	v_add_f32_e32 v70, v110, v70
	v_add_f32_e32 v98, v111, v70
	v_cvt_pk_bf16_f32 v146, v106, v107
	v_cvt_pk_bf16_f32 v147, v108, v109
	ds_read_b64_tr_b16 v[70:71], v228 offset:29696
	ds_read_b64_tr_b16 v[72:73], v228 offset:30208
	s_waitcnt lgkmcnt(12)
	v_mfma_f32_32x32x16_bf16 v[50:65], v[78:81], v[150:153], v[50:65]
	v_add_f32_e32 v78, v112, v98
	v_add_f32_e32 v78, v113, v78
	v_add_f32_e32 v78, v82, v78
	v_add_f32_e32 v98, v83, v78
	v_cvt_pk_bf16_f32 v148, v110, v111
	v_cvt_pk_bf16_f32 v149, v112, v113
	ds_read_b64_tr_b16 v[78:79], v228 offset:26624
	ds_read_b64_tr_b16 v[80:81], v228 offset:27136
	s_waitcnt lgkmcnt(13)
	v_mfma_f32_32x32x16_bf16 v[114:129], v[178:181], v[142:145], v[114:129]
	v_add_f32_e32 v98, v84, v98
	v_add_f32_e32 v98, v85, v98
	v_add_f32_e32 v98, v86, v98
	v_add_f32_e32 v98, v87, v98
	v_cvt_pk_bf16_f32 v138, v82, v83
	v_cvt_pk_bf16_f32 v139, v84, v85
	ds_read_b64_tr_b16 v[82:83], v228 offset:30720
	ds_read_b64_tr_b16 v[84:85], v228 offset:31232
	s_waitcnt lgkmcnt(14)
	v_mfma_f32_32x32x16_bf16 v[50:65], v[174:177], v[142:145], v[50:65]
	v_add_f32_e32 v98, v88, v98
	v_add_f32_e32 v98, v89, v98
	v_add_f32_e32 v98, v90, v98
	v_add_f32_e32 v98, v91, v98
	v_cvt_pk_bf16_f32 v140, v86, v87
	v_cvt_pk_bf16_f32 v141, v88, v89
	ds_read_b64_tr_b16 v[86:87], v228 offset:27648
	ds_read_b64_tr_b16 v[88:89], v228 offset:28160
	s_waitcnt lgkmcnt(14)
	v_mfma_f32_32x32x16_bf16 v[114:129], v[170:173], v[134:137], v[114:129]
	v_add_f32_e32 v98, v92, v98
	v_add_f32_e32 v98, v93, v98
	v_add_f32_e32 v98, v94, v98
	v_add_f32_e32 v98, v95, v98
	v_cvt_pk_bf16_f32 v130, v90, v91
	v_cvt_pk_bf16_f32 v131, v92, v93
	ds_read_b64_tr_b16 v[90:91], v228 offset:31744
	ds_read_b64_tr_b16 v[92:93], v228 offset:32256
	v_mfma_f32_32x32x16_bf16 v[50:65], v[166:169], v[134:137], v[50:65]
	v_add_f32_e32 v98, v96, v98
	v_add_f32_e32 v98, v97, v98
	v_cvt_pk_bf16_f32 v132, v94, v95
	v_cvt_pk_bf16_f32 v133, v96, v97
	s_cmp_lg_u32 0, -1
	s_cselect_b32 s4, 0, 0
	v_lshl_add_u64 v[94:95], v[224:225], 0, s[64:65]
	s_add_i32 s4, s4, s38
	s_add_i32 s5, s4, 0x2000
	s_mov_b32 m0, s5
	s_nop 0
	global_load_lds_dwordx4 v[94:95], off
	v_lshl_add_u64 v[94:95], v[226:227], 0, s[14:15]
	s_add_i32 s4, s4, 0xa000
	s_mov_b32 m0, s4
	s_nop 0
	global_load_lds_dwordx4 v[94:95], off
	v_max_f32_e32 v94, v115, v115
	v_max_f32_e32 v95, v114, v114
	v_max_f32_e32 v94, v95, v94
	v_max3_f32 v95, v116, v117, v51
	v_max3_f32 v94, v94, v50, v52
	v_max3_f32 v94, v94, v53, v118
	v_max3_f32 v95, v95, v120, v121
	v_max3_f32 v94, v94, v119, v54
	v_max3_f32 v95, v95, v56, v57
	v_max3_f32 v94, v94, v55, v122
	v_max3_f32 v95, v95, v124, v125
	v_max3_f32 v94, v94, v123, v58
	v_max3_f32 v95, v95, v60, v61
	v_max3_f32 v94, v94, v59, v126
	v_max3_f32 v95, v95, v128, v129
	v_max3_f32 v94, v94, v127, v62
	v_max3_f32 v95, v95, v64, v65
	v_max3_f32 v94, v94, v63, v95
	v_mov_b32_e32 v95, v94
	s_nop 1
	v_permlane32_swap_b32_e32 v94, v95
	v_max_f32_e32 v94, v94, v95
	v_cmp_lt_f32_e32 vcc, s27, v94
	s_cmp_lg_u64 vcc, 0
	v_add_f32_e32 v221, v221, v98
	s_cselect_b64 s[4:5], -1, 0
	s_cbranch_vccnz .LBB0_602

.LBB0_573:
	ds_read_b64_tr_b16 v[162:163], v228 offset:32768
	ds_read_b64_tr_b16 v[164:165], v228 offset:33280
	s_waitcnt lgkmcnt(9)
	v_mfma_f32_32x32x16_bf16 v[98:113], v[74:77], v[158:161], v[34:49]
	v_add_f32_e32 v66, v114, v115
	v_add_f32_e32 v66, v116, v66
	v_add_f32_e32 v66, v117, v66
	v_add_f32_e32 v66, v118, v66
	v_add_f32_e32 v66, v119, v66
	v_cvt_pk_bf16_f32 v154, v114, v115
	v_cvt_pk_bf16_f32 v155, v116, v117
	ds_read_b64_tr_b16 v[90:91], v228 offset:36864
	ds_read_b64_tr_b16 v[92:93], v228 offset:37376
	v_add_f32_e32 v66, v120, v66
	v_add_f32_e32 v66, v121, v66
	v_add_f32_e32 v66, v122, v66
	v_add_f32_e32 v86, v123, v66
	s_waitcnt lgkmcnt(10)
	v_mfma_f32_32x32x16_bf16 v[66:81], v[182:185], v[158:161], v[34:49]
	v_cvt_pk_bf16_f32 v156, v118, v119
	v_cvt_pk_bf16_f32 v157, v120, v121
	ds_read_b64_tr_b16 v[82:83], v228 offset:33792
	ds_read_b64_tr_b16 v[84:85], v228 offset:34304
	s_waitcnt lgkmcnt(11)
	v_mfma_f32_32x32x16_bf16 v[98:113], v[186:189], v[150:153], v[98:113]
	v_add_f32_e32 v86, v124, v86
	v_add_f32_e32 v86, v125, v86
	v_add_f32_e32 v86, v126, v86
	v_add_f32_e32 v114, v127, v86
	v_cvt_pk_bf16_f32 v146, v122, v123
	v_cvt_pk_bf16_f32 v147, v124, v125
	ds_read_b64_tr_b16 v[86:87], v228 offset:37888
	ds_read_b64_tr_b16 v[88:89], v228 offset:38400
	s_waitcnt lgkmcnt(12)
	v_mfma_f32_32x32x16_bf16 v[66:81], v[94:97], v[150:153], v[66:81]
	v_add_f32_e32 v94, v128, v114
	v_add_f32_e32 v94, v129, v94
	v_add_f32_e32 v94, v50, v94
	v_add_f32_e32 v114, v51, v94
	v_cvt_pk_bf16_f32 v148, v126, v127
	v_cvt_pk_bf16_f32 v149, v128, v129
	ds_read_b64_tr_b16 v[94:95], v228 offset:34816
	ds_read_b64_tr_b16 v[96:97], v228 offset:35328
	s_waitcnt lgkmcnt(13)
	v_mfma_f32_32x32x16_bf16 v[98:113], v[178:181], v[142:145], v[98:113]
	v_add_f32_e32 v114, v52, v114
	v_add_f32_e32 v114, v53, v114
	v_add_f32_e32 v114, v54, v114
	v_add_f32_e32 v114, v55, v114
	v_cvt_pk_bf16_f32 v138, v50, v51
	v_cvt_pk_bf16_f32 v139, v52, v53
	ds_read_b64_tr_b16 v[50:51], v228 offset:38912
	ds_read_b64_tr_b16 v[52:53], v228 offset:39424
	s_waitcnt lgkmcnt(14)
	v_mfma_f32_32x32x16_bf16 v[66:81], v[174:177], v[142:145], v[66:81]
	v_add_f32_e32 v114, v56, v114
	v_add_f32_e32 v114, v57, v114
	v_add_f32_e32 v114, v58, v114
	v_add_f32_e32 v114, v59, v114
	v_cvt_pk_bf16_f32 v140, v54, v55
	v_cvt_pk_bf16_f32 v141, v56, v57
	ds_read_b64_tr_b16 v[54:55], v228 offset:35840
	ds_read_b64_tr_b16 v[56:57], v228 offset:36352
	s_waitcnt lgkmcnt(14)
	v_mfma_f32_32x32x16_bf16 v[98:113], v[170:173], v[134:137], v[98:113]
	v_add_f32_e32 v114, v60, v114
	v_add_f32_e32 v114, v61, v114
	v_add_f32_e32 v114, v62, v114
	v_add_f32_e32 v114, v63, v114
	v_cvt_pk_bf16_f32 v130, v58, v59
	v_cvt_pk_bf16_f32 v131, v60, v61
	ds_read_b64_tr_b16 v[58:59], v228 offset:39936
	ds_read_b64_tr_b16 v[60:61], v228 offset:40448
	v_mfma_f32_32x32x16_bf16 v[66:81], v[166:169], v[134:137], v[66:81]
	v_add_f32_e32 v114, v64, v114
	v_add_f32_e32 v114, v65, v114
	v_cvt_pk_bf16_f32 v132, v62, v63
	v_cvt_pk_bf16_f32 v133, v64, v65
	v_lshl_add_u64 v[62:63], v[222:223], 0, s[68:69]
	s_mov_b32 m0, s37
	s_nop 0
	global_load_lds_dwordx4 v[62:63], off
	v_max_f32_e32 v62, v99, v99
	v_max_f32_e32 v63, v98, v98
	v_max_f32_e32 v62, v63, v62
	s_nop 2
	v_max3_f32 v63, v100, v101, v67
	v_max3_f32 v62, v62, v66, v68
	v_max3_f32 v62, v62, v69, v102
	v_max3_f32 v63, v63, v104, v105
	v_max3_f32 v62, v62, v103, v70
	v_max3_f32 v63, v63, v72, v73
	v_max3_f32 v62, v62, v71, v106
	v_max3_f32 v63, v63, v108, v109
	v_max3_f32 v62, v62, v107, v74
	v_max3_f32 v63, v63, v76, v77
	v_max3_f32 v62, v62, v75, v110
	v_max3_f32 v63, v63, v112, v113
	v_max3_f32 v62, v62, v111, v78
	v_max3_f32 v63, v63, v80, v81
	v_max3_f32 v62, v62, v79, v63
	v_mov_b32_e32 v63, v62
	s_nop 1
	v_permlane32_swap_b32_e32 v62, v63
	v_max_f32_e32 v62, v62, v63
	v_cmp_lt_f32_e32 vcc, s27, v62
	s_cmp_lg_u64 vcc, 0
	v_add_f32_e32 v182, v221, v114
	s_cselect_b64 s[4:5], -1, 0
	s_cbranch_vccnz .LBB0_605

.LBB0_576:
	s_mov_b64 s[4:5], 0x1f4000
	v_lshl_add_u64 v[184:185], v[222:223], 0, s[4:5]
	ds_read_b64_tr_b16 v[118:119], v228 offset:40960
	ds_read_b64_tr_b16 v[120:121], v228 offset:41472
	s_waitcnt lgkmcnt(9)
	v_mfma_f32_32x32x16_bf16 v[82:97], v[62:65], v[158:161], v[34:49]
	v_add_f32_e32 v50, v98, v99
	v_add_f32_e32 v50, v100, v50
	v_add_f32_e32 v50, v101, v50
	v_add_f32_e32 v50, v102, v50
	v_add_f32_e32 v50, v103, v50
	v_cvt_pk_bf16_f32 v154, v98, v99
	v_cvt_pk_bf16_f32 v155, v100, v101
	ds_read_b64_tr_b16 v[114:115], v228 offset:45056
	ds_read_b64_tr_b16 v[116:117], v228 offset:45568
	v_add_f32_e32 v50, v104, v50
	v_add_f32_e32 v50, v105, v50
	v_add_f32_e32 v50, v106, v50
	v_add_f32_e32 v130, v107, v50
	s_waitcnt lgkmcnt(10)
	v_mfma_f32_32x32x16_bf16 v[50:65], v[174:177], v[158:161], v[34:49]
	v_cvt_pk_bf16_f32 v156, v102, v103
	v_cvt_pk_bf16_f32 v157, v104, v105
	ds_read_b64_tr_b16 v[98:99], v228 offset:41984
	ds_read_b64_tr_b16 v[100:101], v228 offset:42496
	s_waitcnt lgkmcnt(11)
	v_mfma_f32_32x32x16_bf16 v[82:97], v[178:181], v[150:153], v[82:97]
	v_add_f32_e32 v102, v108, v130
	v_add_f32_e32 v102, v109, v102
	v_add_f32_e32 v102, v110, v102
	v_add_f32_e32 v130, v111, v102
	v_cvt_pk_bf16_f32 v146, v106, v107
	v_cvt_pk_bf16_f32 v147, v108, v109
	ds_read_b64_tr_b16 v[102:103], v228 offset:46080
	ds_read_b64_tr_b16 v[104:105], v228 offset:46592
	s_waitcnt lgkmcnt(12)
	v_mfma_f32_32x32x16_bf16 v[50:65], v[170:173], v[150:153], v[50:65]
	v_add_f32_e32 v106, v112, v130
	v_add_f32_e32 v106, v113, v106
	v_add_f32_e32 v106, v66, v106
	v_add_f32_e32 v130, v67, v106
	v_cvt_pk_bf16_f32 v148, v110, v111
	v_cvt_pk_bf16_f32 v149, v112, v113
	ds_read_b64_tr_b16 v[106:107], v228 offset:43008
	ds_read_b64_tr_b16 v[108:109], v228 offset:43520
	s_waitcnt lgkmcnt(13)
	v_mfma_f32_32x32x16_bf16 v[82:97], v[166:169], v[142:145], v[82:97]
	v_add_f32_e32 v110, v68, v130
	v_add_f32_e32 v110, v69, v110
	v_add_f32_e32 v110, v70, v110
	v_add_f32_e32 v110, v71, v110
	v_cvt_pk_bf16_f32 v138, v66, v67
	v_cvt_pk_bf16_f32 v139, v68, v69
	ds_read_b64_tr_b16 v[66:67], v228 offset:47104
	ds_read_b64_tr_b16 v[68:69], v228 offset:47616
	s_waitcnt lgkmcnt(14)
	v_mfma_f32_32x32x16_bf16 v[50:65], v[162:165], v[142:145], v[50:65]
	v_add_f32_e32 v110, v72, v110
	v_add_f32_e32 v110, v73, v110
	v_add_f32_e32 v110, v74, v110
	v_add_f32_e32 v110, v75, v110
	v_cvt_pk_bf16_f32 v140, v70, v71
	v_cvt_pk_bf16_f32 v141, v72, v73
	ds_read_b64_tr_b16 v[70:71], v228 offset:44032
	ds_read_b64_tr_b16 v[72:73], v228 offset:44544
	s_waitcnt lgkmcnt(14)
	v_mfma_f32_32x32x16_bf16 v[82:97], v[126:129], v[134:137], v[82:97]
	v_add_f32_e32 v110, v76, v110
	v_add_f32_e32 v110, v77, v110
	v_add_f32_e32 v110, v78, v110
	v_add_f32_e32 v110, v79, v110
	v_cvt_pk_bf16_f32 v130, v74, v75
	v_cvt_pk_bf16_f32 v131, v76, v77
	ds_read_b64_tr_b16 v[74:75], v228 offset:48128
	ds_read_b64_tr_b16 v[76:77], v228 offset:48640
	v_mfma_f32_32x32x16_bf16 v[50:65], v[122:125], v[134:137], v[50:65]
	v_add_f32_e32 v110, v80, v110
	v_add_f32_e32 v110, v81, v110
	v_cvt_pk_bf16_f32 v132, v78, v79
	v_cvt_pk_bf16_f32 v133, v80, v81
	v_lshl_add_u64 v[78:79], v[184:185], 0, s[14:15]
	s_mov_b32 m0, s40
	s_nop 0
	global_load_lds_dwordx4 v[78:79], off
	v_max_f32_e32 v78, v83, v83
	v_max_f32_e32 v79, v82, v82
	v_max_f32_e32 v78, v79, v78
	s_nop 2
	v_max3_f32 v79, v84, v85, v51
	v_max3_f32 v78, v78, v50, v52
	v_max3_f32 v78, v78, v53, v86
	v_max3_f32 v79, v79, v88, v89
	v_max3_f32 v78, v78, v87, v54
	v_max3_f32 v79, v79, v56, v57
	v_max3_f32 v78, v78, v55, v90
	v_max3_f32 v79, v79, v92, v93
	v_max3_f32 v78, v78, v91, v58
	v_max3_f32 v79, v79, v60, v61
	v_max3_f32 v78, v78, v59, v94
	v_max3_f32 v79, v79, v96, v97
	v_max3_f32 v78, v78, v95, v62
	v_max3_f32 v79, v79, v64, v65
	v_max3_f32 v78, v78, v63, v79
	v_mov_b32_e32 v79, v78
	s_nop 1
	v_permlane32_swap_b32_e32 v78, v79
	v_max_f32_e32 v78, v78, v79
	v_cmp_lt_f32_e32 vcc, s27, v78
	s_cmp_lg_u64 vcc, 0
	v_add_f32_e32 v170, v182, v110
	s_cselect_b64 s[4:5], -1, 0
	s_cbranch_vccnz .LBB0_608

.LBB0_999:
	v_readfirstlane_b32 s46, v192
	s_lshr_b32 s79, s46, 6
	s_lshl_b32 s40, s79, 4
	s_mov_b32 s41, s19
	v_lshl_add_u64 v[34:35], v[118:119], 0, s[40:41]
	s_lshr_b32 s40, s46, 2
	v_and_or_b32 v175, s40, 48, v193
	v_or_b32_e32 v0, s64, v175
	s_lshr_b32 s40, s46, 3
	v_lshlrev_b32_e32 v0, 7, v0
	v_mov_b32_e32 v1, v80
	s_and_b32 s40, s40, 0x1fffffe0
	v_lshl_add_u64 v[0:1], s[38:39], 0, v[0:1]
	s_lshl_b32 s40, s40, 1
	v_lshl_add_u64 v[0:1], v[0:1], 0, s[40:41]
	v_mov_b32_e32 v117, v80
	s_and_b64 vcc, exec, s[6:7]
	v_lshl_add_u64 v[36:37], v[0:1], 0, v[116:117]
	s_cbranch_vccnz .LBB0_1005
	s_lshl_b32 s42, s75, 13
	s_mov_b32 s43, s19
	s_lshl_b32 s41, s79, 10
	v_lshl_add_u64 v[0:1], v[34:35], 0, s[42:43]
	s_add_i32 s41, s41, 0
	s_mov_b32 m0, s41
	s_nop 0
	global_load_lds_dwordx4 v[0:1], off
	v_lshl_add_u64 v[0:1], v[36:37], 0, s[42:43]
	s_add_i32 s44, s41, 0xc000
	s_mov_b32 m0, s44
	s_nop 0
	global_load_lds_dwordx4 v[0:1], off
	s_cmp_ge_u32 s75, s71
	s_cbranch_scc0 .LBB0_1074
	s_add_i32 s42, s76, -2
	s_cmp_gt_u32 s42, s71
	s_cbranch_scc0 .LBB0_1075

.LBB0_1004:
	s_lshl_b32 s42, s76, 13
	s_mov_b32 s43, s19
	v_lshl_add_u64 v[0:1], v[34:35], 0, s[42:43]
	s_add_i32 s41, s41, 0x8000
	s_mov_b32 m0, s41
	s_nop 0
	global_load_lds_dwordx4 v[0:1], off
	v_lshl_add_u64 v[0:1], v[36:37], 0, s[42:43]
	s_add_i32 s41, s44, 0x8000
	s_mov_b32 m0, s41
	s_nop 0
	global_load_lds_dwordx4 v[0:1], off

.LBB0_1009:
	s_or_b64 exec, exec, s[42:43]
	s_lshl_b32 s80, s79, 5
	v_or_b32_e32 v0, s65, v191
	v_add_u32_e32 v0, s80, v0
	v_add_u32_e32 v2, s64, v0
	v_mov_b32_e32 v3, v80
	v_lshlrev_b64 v[2:3], 7, v[2:3]
	v_lshl_add_u64 v[2:3], s[36:37], 0, v[2:3]
	v_lshlrev_b32_e32 v4, 1, v104
	v_mov_b32_e32 v5, v80
	v_lshl_add_u64 v[2:3], v[2:3], 0, v[4:5]
	global_load_dwordx4 v[84:87], v[2:3], off
	global_load_dwordx4 v[88:91], v[2:3], off offset:32
	global_load_dwordx4 v[92:95], v[2:3], off offset:64
	global_load_dwordx4 v[96:99], v[2:3], off offset:96
	s_lshl_b32 s42, s79, 10
	s_add_i32 s82, s42, 0
	s_lshl_b32 s41, s79, 3
	s_add_i32 s81, s82, 0xc000
	s_waitcnt vmcnt(0) lgkmcnt(0)
	s_barrier
	s_cmp_ge_u32 s77, s71
	v_readfirstlane_b32 s44, v0
	s_cselect_b64 s[42:43], -1, 0
	s_cmp_lt_u32 s77, s71
	s_cbranch_scc0 .LBB0_1011
	s_lshl_b32 s45, s76, 13
	s_or_b32 s84, s45, 0x2000
	s_mov_b32 s85, s19
	v_lshl_add_u64 v[2:3], v[34:35], 0, s[84:85]
	s_add_i32 s45, s82, 0xa000
	s_mov_b32 m0, s45
	s_nop 0
	global_load_lds_dwordx4 v[2:3], off
	v_lshl_add_u64 v[2:3], v[36:37], 0, s[84:85]
	s_add_i32 s45, s81, 0xa000
	s_mov_b32 m0, s45
	s_nop 0
	global_load_lds_dwordx4 v[2:3], off

.LBB0_1017:
	s_cmp_le_u32 s87, s71
	s_cselect_b64 s[44:45], -1, 0
	s_cmp_gt_u32 s87, s71
	s_cbranch_scc1 .LBB0_1019
	s_lshl_b32 s46, s88, 13
	v_lshl_add_u64 v[48:49], v[122:123], 0, s[42:43]
	s_add_i32 s46, s82, s46
	s_mov_b32 m0, s46
	s_nop 0
	global_load_lds_dwordx4 v[48:49], off
	v_lshl_add_u64 v[48:49], v[120:121], 0, s[42:43]
	s_add_i32 s46, s46, 0xc000
	s_mov_b32 m0, s46
	s_nop 0
	global_load_lds_dwordx4 v[48:49], off

.LBB0_1033:
	s_lshl_b32 s40, s66, 13
	s_mov_b32 s41, s19
	v_lshl_add_u64 v[32:33], v[32:33], 0, s[40:41]
	s_add_i32 s42, s82, 0x8000
	s_mov_b32 m0, s42
	s_nop 0
	global_load_lds_dwordx4 v[32:33], off
	v_lshl_add_u64 v[32:33], v[34:35], 0, s[40:41]
	s_add_i32 s40, s81, 0x8000
	s_mov_b32 m0, s40
	s_nop 0
	global_load_lds_dwordx4 v[32:33], off

.LBB0_1037:
	v_readfirstlane_b32 s46, v192
	s_lshr_b32 s42, s46, 6
	s_lshl_b32 s40, s42, 4
	s_mov_b32 s41, s19
	v_lshl_add_u64 v[34:35], v[118:119], 0, s[40:41]
	s_lshr_b32 s40, s46, 2
	v_and_or_b32 v81, s40, 48, v193
	v_or_b32_e32 v0, s64, v81
	v_lshlrev_b32_e32 v0, 7, v0
	v_mov_b32_e32 v1, v80
	v_lshl_add_u64 v[0:1], s[38:39], 0, v[0:1]
	s_lshr_b32 s38, s46, 3
	s_and_b32 s38, s38, 0x1fffffe0
	s_lshl_b32 s38, s38, 1
	s_mov_b32 s39, s19
	v_lshl_add_u64 v[0:1], v[0:1], 0, s[38:39]
	v_mov_b32_e32 v117, v80
	s_and_b64 vcc, exec, s[6:7]
	v_lshl_add_u64 v[36:37], v[0:1], 0, v[116:117]
	s_cbranch_vccnz .LBB0_1043
	s_lshl_b32 s6, s75, 13
	s_mov_b32 s7, s19
	s_lshl_b32 s39, s42, 10
	v_lshl_add_u64 v[0:1], v[34:35], 0, s[6:7]
	s_add_i32 s39, s39, 0
	s_mov_b32 m0, s39
	s_nop 0
	global_load_lds_dwordx4 v[0:1], off
	v_lshl_add_u64 v[0:1], v[36:37], 0, s[6:7]
	s_add_i32 s40, s39, 0xc000
	s_mov_b32 m0, s40
	s_nop 0
	global_load_lds_dwordx4 v[0:1], off
	s_cmp_ge_u32 s75, s71
	s_cbranch_scc0 .LBB0_1081
	s_add_i32 s6, s76, -2
	s_cmp_gt_u32 s6, s71
	s_cbranch_scc0 .LBB0_1082

.LBB0_1042:
	s_lshl_b32 s6, s76, 13
	s_mov_b32 s7, s19
	v_lshl_add_u64 v[0:1], v[34:35], 0, s[6:7]
	s_add_i32 s39, s39, 0x8000
	s_mov_b32 m0, s39
	s_nop 0
	global_load_lds_dwordx4 v[0:1], off
	v_lshl_add_u64 v[0:1], v[36:37], 0, s[6:7]
	s_add_i32 s6, s40, 0x8000
	s_mov_b32 m0, s6
	s_nop 0
	global_load_lds_dwordx4 v[0:1], off

.LBB0_1047:
	s_or_b64 exec, exec, s[6:7]
	s_lshl_b32 s43, s42, 5
	v_or_b32_e32 v0, s65, v191
	v_add_u32_e32 v0, s43, v0
	v_add_u32_e32 v2, s64, v0
	v_mov_b32_e32 v3, v80
	v_lshlrev_b64 v[2:3], 7, v[2:3]
	v_lshl_add_u64 v[2:3], s[36:37], 0, v[2:3]
	v_lshlrev_b32_e32 v4, 1, v104
	v_mov_b32_e32 v5, v80
	v_lshl_add_u64 v[2:3], v[2:3], 0, v[4:5]
	global_load_dwordx4 v[82:85], v[2:3], off
	global_load_dwordx4 v[86:89], v[2:3], off offset:32
	global_load_dwordx4 v[90:93], v[2:3], off offset:64
	global_load_dwordx4 v[94:97], v[2:3], off offset:96
	s_lshl_b32 s6, s42, 10
	s_add_i32 s45, s6, 0
	s_lshl_b32 s39, s42, 3
	s_add_i32 s44, s45, 0xc000
	s_waitcnt vmcnt(0) lgkmcnt(0)
	s_barrier
	s_cmp_ge_u32 s77, s71
	v_readfirstlane_b32 s36, v0
	s_cselect_b64 s[6:7], -1, 0
	s_cmp_lt_u32 s77, s71
	s_cbranch_scc0 .LBB0_1049
	s_lshl_b32 s37, s76, 13
	s_or_b32 s40, s37, 0x2000
	s_mov_b32 s41, s19
	v_lshl_add_u64 v[2:3], v[34:35], 0, s[40:41]
	s_add_i32 s37, s45, 0xa000
	s_mov_b32 m0, s37
	s_nop 0
	global_load_lds_dwordx4 v[2:3], off
	v_lshl_add_u64 v[2:3], v[36:37], 0, s[40:41]
	s_add_i32 s37, s44, 0xa000
	s_mov_b32 m0, s37
	s_nop 0
	global_load_lds_dwordx4 v[2:3], off

.LBB0_1055:
	s_cmp_le_u32 s70, s71
	s_cselect_b64 s[36:37], -1, 0
	s_cmp_gt_u32 s70, s71
	s_cbranch_scc1 .LBB0_1057
	s_lshl_b32 s40, s74, 13
	v_lshl_add_u64 v[48:49], v[118:119], 0, s[6:7]
	s_add_i32 s40, s45, s40
	s_mov_b32 m0, s40
	s_nop 0
	global_load_lds_dwordx4 v[48:49], off
	v_lshl_add_u64 v[48:49], v[98:99], 0, s[6:7]
	s_add_i32 s40, s40, 0xc000
	s_mov_b32 m0, s40
	s_nop 0
	global_load_lds_dwordx4 v[48:49], off

.LBB0_1071:
	s_lshl_b32 s18, s66, 13
	v_lshl_add_u64 v[32:33], v[32:33], 0, s[18:19]
	s_add_i32 s6, s45, 0x8000
	s_mov_b32 m0, s6
	s_nop 0
	global_load_lds_dwordx4 v[32:33], off
	v_lshl_add_u64 v[32:33], v[34:35], 0, s[18:19]
	s_add_i32 s6, s44, 0x8000
	s_mov_b32 m0, s6
	s_nop 0
	global_load_lds_dwordx4 v[32:33], off

.LBB0_1074:
	s_add_i32 s42, s76, -3
	s_mov_b32 s43, s19
	s_lshl_b64 s[42:43], s[42:43], 13
	v_lshl_add_u64 v[0:1], v[34:35], 0, s[42:43]
	s_add_i32 s45, s41, 0x2000
	s_mov_b32 m0, s45
	s_nop 0
	global_load_lds_dwordx4 v[0:1], off
	v_lshl_add_u64 v[0:1], v[36:37], 0, s[42:43]
	s_add_i32 s42, s41, 0xe000
	s_mov_b32 m0, s42
	s_nop 0
	global_load_lds_dwordx4 v[0:1], off
	s_add_i32 s42, s76, -2
	s_cmp_gt_u32 s42, s71
	s_cbranch_scc1 .LBB0_1002
.LBB0_1075:
	s_mov_b32 s43, s19
	s_lshl_b64 s[42:43], s[42:43], 13
	v_lshl_add_u64 v[0:1], v[34:35], 0, s[42:43]
	s_add_i32 s45, s41, 0x4000
	s_mov_b32 m0, s45
	s_nop 0
	global_load_lds_dwordx4 v[0:1], off
	v_lshl_add_u64 v[0:1], v[36:37], 0, s[42:43]
	s_add_i32 s42, s44, 0x4000
	s_mov_b32 m0, s42
	s_nop 0
	global_load_lds_dwordx4 v[0:1], off
	s_add_i32 s42, s76, -1
	s_cmp_gt_u32 s42, s71
	s_cbranch_scc1 .LBB0_1003
.LBB0_1076:
	s_mov_b32 s43, s19
	s_lshl_b64 s[42:43], s[42:43], 13
	v_lshl_add_u64 v[0:1], v[34:35], 0, s[42:43]
	s_add_i32 s45, s41, 0x6000
	s_mov_b32 m0, s45
	s_nop 0
	global_load_lds_dwordx4 v[0:1], off
	v_lshl_add_u64 v[0:1], v[36:37], 0, s[42:43]
	s_add_i32 s42, s44, 0x6000
	s_mov_b32 m0, s42
	s_nop 0
	global_load_lds_dwordx4 v[0:1], off
	s_cmp_gt_u32 s77, s71
	s_cbranch_scc0 .LBB0_1004
	s_branch .LBB0_1005
.LBB0_1077:
	s_lshl_b32 s40, s69, 13
	s_mov_b32 s41, s19
	v_lshl_add_u64 v[36:37], v[32:33], 0, s[40:41]
	s_mov_b32 m0, s82
	s_nop 0
	global_load_lds_dwordx4 v[36:37], off
	v_lshl_add_u64 v[36:37], v[34:35], 0, s[40:41]
	s_mov_b32 m0, s81
	s_nop 0
	global_load_lds_dwordx4 v[36:37], off
	s_cmp_ge_i32 s69, s68
	s_cbranch_scc1 .LBB0_1030
.LBB0_1078:
	s_add_i32 s40, s66, -3
	s_mov_b32 s41, s19
	s_lshl_b64 s[40:41], s[40:41], 13
	v_lshl_add_u64 v[36:37], v[32:33], 0, s[40:41]
	s_add_i32 s42, s82, 0x2000
	s_mov_b32 m0, s42
	s_nop 0
	global_load_lds_dwordx4 v[36:37], off
	v_lshl_add_u64 v[36:37], v[34:35], 0, s[40:41]
	s_add_i32 s40, s82, 0xe000
	s_mov_b32 m0, s40
	s_nop 0
	global_load_lds_dwordx4 v[36:37], off
	s_add_i32 s40, s66, -2
	s_cmp_gt_i32 s40, s68
	s_cbranch_scc1 .LBB0_1031
.LBB0_1079:
	s_mov_b32 s41, s19
	s_lshl_b64 s[40:41], s[40:41], 13
	v_lshl_add_u64 v[36:37], v[32:33], 0, s[40:41]
	s_add_i32 s42, s82, 0x4000
	s_mov_b32 m0, s42
	s_nop 0
	global_load_lds_dwordx4 v[36:37], off
	v_lshl_add_u64 v[36:37], v[34:35], 0, s[40:41]
	s_add_i32 s40, s81, 0x4000
	s_mov_b32 m0, s40
	s_nop 0
	global_load_lds_dwordx4 v[36:37], off
	s_add_i32 s40, s66, -1
	s_cmp_gt_i32 s40, s68
	s_cbranch_scc1 .LBB0_1032
.LBB0_1080:
	s_mov_b32 s41, s19
	s_lshl_b64 s[40:41], s[40:41], 13
	v_lshl_add_u64 v[36:37], v[32:33], 0, s[40:41]
	s_add_i32 s42, s82, 0x6000
	s_mov_b32 m0, s42
	s_nop 0
	global_load_lds_dwordx4 v[36:37], off
	v_lshl_add_u64 v[36:37], v[34:35], 0, s[40:41]
	s_add_i32 s40, s81, 0x6000
	s_mov_b32 m0, s40
	s_nop 0
	global_load_lds_dwordx4 v[36:37], off
	s_cmp_gt_u32 s67, s68
	s_cbranch_scc0 .LBB0_1033
	s_branch .LBB0_1034
.LBB0_1081:
	s_add_i32 s6, s76, -3
	s_mov_b32 s7, s19
	s_lshl_b64 s[6:7], s[6:7], 13
	v_lshl_add_u64 v[0:1], v[34:35], 0, s[6:7]
	s_add_i32 s41, s39, 0x2000
	s_mov_b32 m0, s41
	s_nop 0
	global_load_lds_dwordx4 v[0:1], off
	v_lshl_add_u64 v[0:1], v[36:37], 0, s[6:7]
	s_add_i32 s6, s39, 0xe000
	s_mov_b32 m0, s6
	s_nop 0
	global_load_lds_dwordx4 v[0:1], off
	s_add_i32 s6, s76, -2
	s_cmp_gt_u32 s6, s71
	s_cbranch_scc1 .LBB0_1040
.LBB0_1082:
	s_mov_b32 s7, s19
	s_lshl_b64 s[6:7], s[6:7], 13
	v_lshl_add_u64 v[0:1], v[34:35], 0, s[6:7]
	s_add_i32 s41, s39, 0x4000
	s_mov_b32 m0, s41
	s_nop 0
	global_load_lds_dwordx4 v[0:1], off
	v_lshl_add_u64 v[0:1], v[36:37], 0, s[6:7]
	s_add_i32 s6, s40, 0x4000
	s_mov_b32 m0, s6
	s_nop 0
	global_load_lds_dwordx4 v[0:1], off
	s_add_i32 s6, s76, -1
	s_cmp_gt_u32 s6, s71
	s_cbranch_scc1 .LBB0_1041
.LBB0_1083:
	s_mov_b32 s7, s19
	s_lshl_b64 s[6:7], s[6:7], 13
	v_lshl_add_u64 v[0:1], v[34:35], 0, s[6:7]
	s_add_i32 s41, s39, 0x6000
	s_mov_b32 m0, s41
	s_nop 0
	global_load_lds_dwordx4 v[0:1], off
	v_lshl_add_u64 v[0:1], v[36:37], 0, s[6:7]
	s_add_i32 s6, s40, 0x6000
	s_mov_b32 m0, s6
	s_nop 0
	global_load_lds_dwordx4 v[0:1], off
	s_cmp_gt_u32 s77, s71
	s_cbranch_scc0 .LBB0_1042
	s_branch .LBB0_1043
.LBB0_1084:
	s_lshl_b32 s18, s69, 13
	v_lshl_add_u64 v[36:37], v[32:33], 0, s[18:19]
	s_mov_b32 m0, s45
	s_nop 0
	global_load_lds_dwordx4 v[36:37], off
	v_lshl_add_u64 v[36:37], v[34:35], 0, s[18:19]
	s_mov_b32 m0, s44
	s_nop 0
	global_load_lds_dwordx4 v[36:37], off
	s_cmp_ge_i32 s69, s68
	s_cbranch_scc1 .LBB0_1068
.LBB0_1085:
	s_add_i32 s18, s66, -3
	s_lshl_b64 s[6:7], s[18:19], 13
	v_lshl_add_u64 v[36:37], v[32:33], 0, s[6:7]
	s_add_i32 s18, s45, 0x2000
	s_mov_b32 m0, s18
	s_nop 0
	global_load_lds_dwordx4 v[36:37], off
	v_lshl_add_u64 v[36:37], v[34:35], 0, s[6:7]
	s_add_i32 s6, s45, 0xe000
	s_mov_b32 m0, s6
	s_nop 0
	global_load_lds_dwordx4 v[36:37], off
	s_add_i32 s18, s66, -2
	s_cmp_gt_i32 s18, s68
	s_cbranch_scc1 .LBB0_1069
.LBB0_1086:
	s_lshl_b64 s[6:7], s[18:19], 13
	v_lshl_add_u64 v[36:37], v[32:33], 0, s[6:7]
	s_add_i32 s18, s45, 0x4000
	s_mov_b32 m0, s18
	s_nop 0
	global_load_lds_dwordx4 v[36:37], off
	v_lshl_add_u64 v[36:37], v[34:35], 0, s[6:7]
	s_add_i32 s6, s44, 0x4000
	s_mov_b32 m0, s6
	s_nop 0
	global_load_lds_dwordx4 v[36:37], off
	s_add_i32 s18, s66, -1
	s_cmp_gt_i32 s18, s68
	s_cbranch_scc1 .LBB0_1070
.LBB0_1087:
	s_lshl_b64 s[6:7], s[18:19], 13
	v_lshl_add_u64 v[36:37], v[32:33], 0, s[6:7]
	s_add_i32 s18, s45, 0x6000
	s_mov_b32 m0, s18
	s_nop 0
	global_load_lds_dwordx4 v[36:37], off
	v_lshl_add_u64 v[36:37], v[34:35], 0, s[6:7]
	s_add_i32 s6, s44, 0x6000
	s_mov_b32 m0, s6
	s_nop 0
	global_load_lds_dwordx4 v[36:37], off
	s_cmp_gt_u32 s67, s68
	s_cbranch_scc0 .LBB0_1071
	s_branch .LBB0_1072
